# v1 + end-of-MFMA-block s_barrier moved up by one MFMA in the 4 GEMM K-loops (partner half released one MFMA early)
# speedup vs baseline: 1.0069x; 1.0069x over previous
; #define PG8_STAGE(bufoff, gbase, voff) do { _Pragma("unroll") for (int _i = 0; _i < 2; ++_i) \
;         __builtin_amdgcn_global_load_lds((const unsigned*)((const char*)(gbase) + (voff)[_i]), (PG8_LAS unsigned*)(lds + (bufoff) + ldsw + _i * 8192), 16, 0, 0); } while (0)
; #define PG8_LDA(dst, b, h) do { _Pragma("unroll") for (int m = 0; m < 4; ++m) _Pragma("unroll") for (int k = 0; k < 2; ++k) dst[m][k] = *(const PG8_LAS bf16x8*)(lds + PG8_SA(b, h) + aoff + m * 2048 + k * 1024); } while (0)
; #define PG8_LDB(dst, b, h) do { _Pragma("unroll") for (int n = 0; n < 2; ++n) _Pragma("unroll") for (int k = 0; k < 2; ++k) dst[n][k] = *(const PG8_LAS bf16x8*)(lds + PG8_SB(b, h) + boff + n * 2048 + k * 1024); } while (0)
; #define PG8_MMA(ai, bj, At, Bt) do { __builtin_amdgcn_s_setprio(1); _Pragma("unroll") for (int m = 0; m < 4; ++m) _Pragma("unroll") for (int n = 0; n < 2; ++n) _Pragma("unroll") for (int k = 0; k < 2; ++k) \
;         acc[ai][bj][m][n] = __builtin_amdgcn_mfma_f32_16x16x32_bf16(Bt[n][k], At[m][k], acc[ai][bj][m][n], 0, 0, 0); __builtin_amdgcn_s_setprio(0); } while (0)
; #define PG8_WAIT_V(n) asm volatile("s_waitcnt vmcnt(" #n ")" ::: "memory")
; #define PG8_WAIT_L(n) asm volatile("s_waitcnt lgkmcnt(" #n ")" ::: "memory")
; #define PG8_BAR __builtin_amdgcn_s_barrier()
; #define PG8_SCHED __builtin_amdgcn_sched_barrier(0)
; template <class Epi, class Sched, bool ALIGN_EPI = false, bool SP2 = false>
; __device__ __forceinline__ void gemm_phase(PG8_LAS unsigned char* lds, const Gemm g, const Sched& S, const Epi& E, int tid_in) {
;     ...
;             PG8_LDB(B0, 0, 0); PG8_LDB(B1, 0, 1); PG8_SCHED; PG8_LDA(At, 0, 0); PG8_STAGE(PG8_SA(1, 1), a1 + hstep, voffA);
;             PG8_WAIT_V(8); PG8_WAIT_L(0); PG8_BAR; PG8_MMA(0, 0, At, B0); PG8_MMA(0, 1, At, B1); PG8_BAR; PG8_SCHED;
;             PG8_LDA(At, 0, 1); PG8_STAGE(PG8_SB(0, 0), b2, voffB); PG8_STAGE(PG8_SB(0, 1), b2 + hstep, voffB); PG8_STAGE(PG8_SA(0, 0), a2, voffA);
;             PG8_WAIT_V(8); PG8_WAIT_L(0); PG8_BAR; PG8_MMA(1, 0, At, B0); PG8_MMA(1, 1, At, B1); PG8_BAR; PG8_SCHED;
.LBB0_158:
	v_or_b32_e32 v32, 0x10000, v194
	v_add_u32_e32 v36, 0x10400, v194
	v_add_u32_e32 v44, 0x10800, v194
	v_add_u32_e32 v48, 0x10c00, v194
	v_or_b32_e32 v81, 0x14000, v194
	v_add_u32_e32 v162, 0x14400, v194
	ds_read_b128 v[32:35], v32
	ds_read_b128 v[36:39], v36
	ds_read_b128 v[44:47], v44
	ds_read_b128 v[48:51], v48
	ds_read_b128 v[158:161], v81
	ds_read_b128 v[162:165], v162
	v_add_u32_e32 v81, 0x14800, v194
	v_add_u32_e32 v170, 0x14c00, v194
	ds_read_b128 v[166:169], v81
	ds_read_b128 v[170:173], v170
	s_add_u32 s29, s84, 0xfffc0080
	s_addc_u32 s31, s85, -1
	s_cmp_eq_u32 s27, 12
	s_cselect_b32 s89, s21, s31
	s_cselect_b32 s88, s22, s29
	s_cselect_b32 s87, s23, s26
	s_cselect_b32 s86, s24, s25
	s_mov_b32 m0, s63
	v_lshl_add_u64 v[174:175], s[84:85], 0, v[154:155]
	ds_read_b128 v[182:185], v177
	ds_read_b128 v[200:203], v177 offset:1024
	ds_read_b128 v[204:207], v177 offset:2048
	ds_read_b128 v[208:211], v177 offset:3072
	ds_read_b128 v[212:215], v177 offset:4096
	ds_read_b128 v[216:219], v177 offset:5120
	ds_read_b128 v[226:229], v177 offset:6144
	ds_read_b128 v[232:235], v177 offset:7168
	global_load_lds_dwordx4 v[174:175], off
	v_lshl_add_u64 v[174:175], s[84:85], 0, v[156:157]
	s_mov_b32 m0, s62
	s_nop 0
	global_load_lds_dwordx4 v[174:175], off
	s_waitcnt vmcnt(8)
	s_waitcnt lgkmcnt(0)
	s_barrier
	s_setprio 1
	s_waitcnt lgkmcnt(0)
	v_mfma_f32_16x16x32_bf16 v[142:145], v[32:35], v[182:185], v[142:145]
	v_mfma_f32_16x16x32_bf16 v[138:141], v[44:47], v[182:185], v[138:141]
	v_mfma_f32_16x16x32_bf16 v[126:129], v[32:35], v[204:207], v[126:129]
	v_mfma_f32_16x16x32_bf16 v[122:125], v[44:47], v[204:207], v[122:125]
	v_mfma_f32_16x16x32_bf16 v[110:113], v[32:35], v[212:215], v[110:113]
	v_mfma_f32_16x16x32_bf16 v[106:109], v[44:47], v[212:215], v[106:109]
	v_mfma_f32_16x16x32_bf16 v[94:97], v[32:35], v[226:229], v[94:97]
	v_mfma_f32_16x16x32_bf16 v[90:93], v[44:47], v[226:229], v[90:93]
	v_mfma_f32_16x16x32_bf16 v[142:145], v[36:39], v[200:203], v[142:145]
	v_mfma_f32_16x16x32_bf16 v[138:141], v[48:51], v[200:203], v[138:141]
	v_mfma_f32_16x16x32_bf16 v[126:129], v[36:39], v[208:211], v[126:129]
	v_mfma_f32_16x16x32_bf16 v[122:125], v[48:51], v[208:211], v[122:125]
	v_mfma_f32_16x16x32_bf16 v[110:113], v[36:39], v[216:219], v[110:113]
	v_mfma_f32_16x16x32_bf16 v[106:109], v[48:51], v[216:219], v[106:109]
	v_mfma_f32_16x16x32_bf16 v[94:97], v[36:39], v[232:235], v[94:97]
	v_mfma_f32_16x16x32_bf16 v[90:93], v[48:51], v[232:235], v[90:93]
	s_setprio 0
	s_setprio 1
	v_mfma_f32_16x16x32_bf16 v[134:137], v[158:161], v[182:185], v[134:137]
	v_mfma_f32_16x16x32_bf16 v[130:133], v[166:169], v[182:185], v[130:133]
	v_mfma_f32_16x16x32_bf16 v[118:121], v[158:161], v[204:207], v[118:121]
	v_mfma_f32_16x16x32_bf16 v[114:117], v[166:169], v[204:207], v[114:117]
	v_mfma_f32_16x16x32_bf16 v[102:105], v[158:161], v[212:215], v[102:105]
	v_mfma_f32_16x16x32_bf16 v[98:101], v[166:169], v[212:215], v[98:101]
	v_mfma_f32_16x16x32_bf16 v[86:89], v[158:161], v[226:229], v[86:89]
	v_mfma_f32_16x16x32_bf16 v[82:85], v[166:169], v[226:229], v[82:85]
	v_mfma_f32_16x16x32_bf16 v[134:137], v[162:165], v[200:203], v[134:137]
	v_mfma_f32_16x16x32_bf16 v[130:133], v[170:173], v[200:203], v[130:133]
	v_mfma_f32_16x16x32_bf16 v[118:121], v[162:165], v[208:211], v[118:121]
	v_mfma_f32_16x16x32_bf16 v[114:117], v[170:173], v[208:211], v[114:117]
	v_mfma_f32_16x16x32_bf16 v[102:105], v[162:165], v[216:219], v[102:105]
	v_mfma_f32_16x16x32_bf16 v[98:101], v[170:173], v[216:219], v[98:101]
	v_mfma_f32_16x16x32_bf16 v[86:89], v[162:165], v[232:235], v[86:89]
	s_barrier
	v_mfma_f32_16x16x32_bf16 v[82:85], v[170:173], v[232:235], v[82:85]
	s_setprio 0
	s_mov_b32 m0, s43
	v_lshl_add_u64 v[174:175], s[86:87], 0, v[148:149]
	s_add_u32 s58, s86, 0x40000
	ds_read_b128 v[182:185], v177 offset:16384
	ds_read_b128 v[200:203], v177 offset:17408
	ds_read_b128 v[204:207], v177 offset:18432
	ds_read_b128 v[208:211], v177 offset:19456
	ds_read_b128 v[212:215], v177 offset:20480
	ds_read_b128 v[216:219], v177 offset:21504
	ds_read_b128 v[226:229], v177 offset:22528
	ds_read_b128 v[232:235], v177 offset:23552
	global_load_lds_dwordx4 v[174:175], off
	v_lshl_add_u64 v[178:179], s[86:87], 0, v[152:153]
	s_mov_b32 m0, s92
	s_addc_u32 s59, s87, 0
	global_load_lds_dwordx4 v[178:179], off
	v_lshl_add_u64 v[180:181], s[58:59], 0, v[148:149]
	s_mov_b32 m0, s93
	v_lshl_add_u64 v[236:237], s[88:89], 0, v[150:151]
	global_load_lds_dwordx4 v[180:181], off
	v_lshl_add_u64 v[180:181], s[58:59], 0, v[152:153]
	s_mov_b32 m0, s94
	s_nop 0
	global_load_lds_dwordx4 v[180:181], off
	v_lshl_add_u64 v[180:181], s[88:89], 0, v[146:147]
	s_mov_b32 m0, s70
	s_nop 0
	global_load_lds_dwordx4 v[180:181], off
	s_mov_b32 m0, s95
	s_nop 0
	global_load_lds_dwordx4 v[236:237], off
	s_waitcnt vmcnt(8)
	s_waitcnt lgkmcnt(0)
	s_barrier
; #define PG8_STAGE(bufoff, gbase, voff) do { _Pragma("unroll") for (int _i = 0; _i < 2; ++_i) \
;         __builtin_amdgcn_global_load_lds((const unsigned*)((const char*)(gbase) + (voff)[_i]), (PG8_LAS unsigned*)(lds + (bufoff) + ldsw + _i * 8192), 16, 0, 0); } while (0)
; #define PG8_LDA(dst, b, h) do { _Pragma("unroll") for (int m = 0; m < 4; ++m) _Pragma("unroll") for (int k = 0; k < 2; ++k) dst[m][k] = *(const PG8_LAS bf16x8*)(lds + PG8_SA(b, h) + aoff + m * 2048 + k * 1024); } while (0)
; #define PG8_LDB(dst, b, h) do { _Pragma("unroll") for (int n = 0; n < 2; ++n) _Pragma("unroll") for (int k = 0; k < 2; ++k) dst[n][k] = *(const PG8_LAS bf16x8*)(lds + PG8_SB(b, h) + boff + n * 2048 + k * 1024); } while (0)
; #define PG8_MMA(ai, bj, At, Bt) do { __builtin_amdgcn_s_setprio(1); _Pragma("unroll") for (int m = 0; m < 4; ++m) _Pragma("unroll") for (int n = 0; n < 2; ++n) _Pragma("unroll") for (int k = 0; k < 2; ++k) \
;         acc[ai][bj][m][n] = __builtin_amdgcn_mfma_f32_16x16x32_bf16(Bt[n][k], At[m][k], acc[ai][bj][m][n], 0, 0, 0); __builtin_amdgcn_s_setprio(0); } while (0)
; #define PG8_WAIT_V(n) asm volatile("s_waitcnt vmcnt(" #n ")" ::: "memory")
; #define PG8_WAIT_L(n) asm volatile("s_waitcnt lgkmcnt(" #n ")" ::: "memory")
; #define PG8_BAR __builtin_amdgcn_s_barrier()
; #define PG8_SCHED __builtin_amdgcn_sched_barrier(0)
; template <class Epi, class Sched, bool ALIGN_EPI = false, bool SP2 = false>
; __device__ __forceinline__ void gemm_phase(PG8_LAS unsigned char* lds, const Gemm g, const Sched& S, const Epi& E, int tid_in) {
;     ...
;             PG8_WAIT_V(8); PG8_WAIT_L(0); PG8_BAR; PG8_MMA(1, 0, At, B0); PG8_MMA(1, 1, At, B1); PG8_BAR; PG8_SCHED;
;             PG8_LDB(B0, 1, 0); PG8_LDB(B1, 1, 1); PG8_SCHED; PG8_LDA(At, 1, 0); PG8_STAGE(PG8_SA(0, 1), a2 + hstep, voffA);
;             PG8_WAIT_V(8); PG8_WAIT_L(0); PG8_BAR; PG8_MMA(0, 0, At, B0); PG8_MMA(0, 1, At, B1); PG8_BAR; PG8_SCHED;
	s_setprio 1
	s_waitcnt lgkmcnt(0)
	v_mfma_f32_16x16x32_bf16 v[76:79], v[32:35], v[182:185], v[76:79]
	v_mfma_f32_16x16x32_bf16 v[72:75], v[44:47], v[182:185], v[72:75]
	v_mfma_f32_16x16x32_bf16 v[60:63], v[32:35], v[204:207], v[60:63]
	v_mfma_f32_16x16x32_bf16 v[56:59], v[44:47], v[204:207], v[56:59]
	v_mfma_f32_16x16x32_bf16 v[28:31], v[32:35], v[212:215], v[28:31]
	v_mfma_f32_16x16x32_bf16 v[24:27], v[44:47], v[212:215], v[24:27]
	v_mfma_f32_16x16x32_bf16 v[12:15], v[32:35], v[226:229], v[12:15]
	v_mfma_f32_16x16x32_bf16 v[8:11], v[44:47], v[226:229], v[8:11]
	v_mfma_f32_16x16x32_bf16 v[76:79], v[36:39], v[200:203], v[76:79]
	v_mfma_f32_16x16x32_bf16 v[72:75], v[48:51], v[200:203], v[72:75]
	v_mfma_f32_16x16x32_bf16 v[60:63], v[36:39], v[208:211], v[60:63]
	v_mfma_f32_16x16x32_bf16 v[56:59], v[48:51], v[208:211], v[56:59]
	v_mfma_f32_16x16x32_bf16 v[28:31], v[36:39], v[216:219], v[28:31]
	v_mfma_f32_16x16x32_bf16 v[24:27], v[48:51], v[216:219], v[24:27]
	v_mfma_f32_16x16x32_bf16 v[12:15], v[36:39], v[232:235], v[12:15]
	v_mfma_f32_16x16x32_bf16 v[8:11], v[48:51], v[232:235], v[8:11]
	s_setprio 0
	s_setprio 1
	v_mfma_f32_16x16x32_bf16 v[40:43], v[166:169], v[204:207], v[40:43]
	v_mfma_f32_16x16x32_bf16 v[20:23], v[158:161], v[212:215], v[20:23]
	v_mfma_f32_16x16x32_bf16 v[16:19], v[166:169], v[212:215], v[16:19]
	v_mfma_f32_16x16x32_bf16 v[4:7], v[158:161], v[226:229], v[4:7]
	v_mfma_f32_16x16x32_bf16 v[0:3], v[166:169], v[226:229], v[0:3]
	v_mfma_f32_16x16x32_bf16 v[32:35], v[158:161], v[182:185], v[68:71]
	v_mfma_f32_16x16x32_bf16 v[36:39], v[166:169], v[182:185], v[64:67]
	v_mfma_f32_16x16x32_bf16 v[44:47], v[158:161], v[204:207], v[52:55]
	v_mfma_f32_16x16x32_bf16 v[40:43], v[170:173], v[208:211], v[40:43]
	v_mfma_f32_16x16x32_bf16 v[20:23], v[162:165], v[216:219], v[20:23]
	v_mfma_f32_16x16x32_bf16 v[16:19], v[170:173], v[216:219], v[16:19]
	v_mfma_f32_16x16x32_bf16 v[4:7], v[162:165], v[232:235], v[4:7]
	v_mfma_f32_16x16x32_bf16 v[0:3], v[170:173], v[232:235], v[0:3]
	v_mfma_f32_16x16x32_bf16 v[32:35], v[162:165], v[200:203], v[32:35]
	v_mfma_f32_16x16x32_bf16 v[36:39], v[170:173], v[200:203], v[36:39]
	s_barrier
	v_mfma_f32_16x16x32_bf16 v[44:47], v[162:165], v[208:211], v[44:47]
	s_setprio 0
	v_or_b32_e32 v48, 0x18000, v194
	v_add_u32_e32 v52, 0x18400, v194
	v_add_u32_e32 v64, 0x18800, v194
	v_add_u32_e32 v68, 0x18c00, v194
	v_or_b32_e32 v81, 0x1c000, v194
	v_add_u32_e32 v162, 0x1c400, v194
	ds_read_b128 v[48:51], v48
	ds_read_b128 v[52:55], v52
	ds_read_b128 v[64:67], v64
	ds_read_b128 v[68:71], v68
	ds_read_b128 v[158:161], v81
	ds_read_b128 v[162:165], v162
	v_add_u32_e32 v81, 0x1c800, v194
	v_add_u32_e32 v170, 0x1cc00, v194
	ds_read_b128 v[166:169], v81
	ds_read_b128 v[170:173], v170
	s_add_u32 s58, s88, 0x40000
	s_addc_u32 s59, s89, 0
	s_mov_b32 m0, s57
	v_lshl_add_u64 v[238:239], s[58:59], 0, v[146:147]
	ds_read_b128 v[182:185], v177 offset:32768
	ds_read_b128 v[200:203], v177 offset:33792
	ds_read_b128 v[204:207], v177 offset:34816
	ds_read_b128 v[208:211], v177 offset:35840
	ds_read_b128 v[212:215], v177 offset:36864
	ds_read_b128 v[216:219], v177 offset:37888
	ds_read_b128 v[226:229], v177 offset:38912
	ds_read_b128 v[232:235], v177 offset:39936
	global_load_lds_dwordx4 v[238:239], off
	v_lshl_add_u64 v[238:239], s[58:59], 0, v[150:151]
	s_mov_b32 m0, s52
	s_nop 0
	global_load_lds_dwordx4 v[238:239], off
	s_waitcnt vmcnt(8)
	s_waitcnt lgkmcnt(0)
	s_barrier
	s_setprio 1
	s_waitcnt lgkmcnt(0)
	v_mfma_f32_16x16x32_bf16 v[142:145], v[48:51], v[182:185], v[142:145]
	v_mfma_f32_16x16x32_bf16 v[138:141], v[64:67], v[182:185], v[138:141]
	v_mfma_f32_16x16x32_bf16 v[126:129], v[48:51], v[204:207], v[126:129]
	v_mfma_f32_16x16x32_bf16 v[122:125], v[64:67], v[204:207], v[122:125]
	v_mfma_f32_16x16x32_bf16 v[110:113], v[48:51], v[212:215], v[110:113]
	v_mfma_f32_16x16x32_bf16 v[106:109], v[64:67], v[212:215], v[106:109]
	v_mfma_f32_16x16x32_bf16 v[94:97], v[48:51], v[226:229], v[94:97]
	v_mfma_f32_16x16x32_bf16 v[90:93], v[64:67], v[226:229], v[90:93]
	v_mfma_f32_16x16x32_bf16 v[142:145], v[52:55], v[200:203], v[142:145]
	v_mfma_f32_16x16x32_bf16 v[138:141], v[68:71], v[200:203], v[138:141]
	v_mfma_f32_16x16x32_bf16 v[126:129], v[52:55], v[208:211], v[126:129]
	v_mfma_f32_16x16x32_bf16 v[122:125], v[68:71], v[208:211], v[122:125]
	v_mfma_f32_16x16x32_bf16 v[110:113], v[52:55], v[216:219], v[110:113]
	v_mfma_f32_16x16x32_bf16 v[106:109], v[68:71], v[216:219], v[106:109]
	v_mfma_f32_16x16x32_bf16 v[94:97], v[52:55], v[232:235], v[94:97]
	v_mfma_f32_16x16x32_bf16 v[90:93], v[68:71], v[232:235], v[90:93]
	s_setprio 0
	s_setprio 1
	v_mfma_f32_16x16x32_bf16 v[134:137], v[158:161], v[182:185], v[134:137]
	v_mfma_f32_16x16x32_bf16 v[130:133], v[166:169], v[182:185], v[130:133]
	v_mfma_f32_16x16x32_bf16 v[118:121], v[158:161], v[204:207], v[118:121]
	v_mfma_f32_16x16x32_bf16 v[114:117], v[166:169], v[204:207], v[114:117]
	v_mfma_f32_16x16x32_bf16 v[102:105], v[158:161], v[212:215], v[102:105]
	v_mfma_f32_16x16x32_bf16 v[98:101], v[166:169], v[212:215], v[98:101]
	v_mfma_f32_16x16x32_bf16 v[86:89], v[158:161], v[226:229], v[86:89]
	v_mfma_f32_16x16x32_bf16 v[82:85], v[166:169], v[226:229], v[82:85]
	v_mfma_f32_16x16x32_bf16 v[134:137], v[162:165], v[200:203], v[134:137]
	v_mfma_f32_16x16x32_bf16 v[130:133], v[170:173], v[200:203], v[130:133]
	v_mfma_f32_16x16x32_bf16 v[118:121], v[162:165], v[208:211], v[118:121]
	v_mfma_f32_16x16x32_bf16 v[114:117], v[170:173], v[208:211], v[114:117]
	v_mfma_f32_16x16x32_bf16 v[102:105], v[162:165], v[216:219], v[102:105]
	v_mfma_f32_16x16x32_bf16 v[98:101], v[170:173], v[216:219], v[98:101]
	v_mfma_f32_16x16x32_bf16 v[86:89], v[162:165], v[232:235], v[86:89]
	s_barrier
; #define PG8_STAGE(bufoff, gbase, voff) do { _Pragma("unroll") for (int _i = 0; _i < 2; ++_i) \
;         __builtin_amdgcn_global_load_lds((const unsigned*)((const char*)(gbase) + (voff)[_i]), (PG8_LAS unsigned*)(lds + (bufoff) + ldsw + _i * 8192), 16, 0, 0); } while (0)
; #define PG8_LDA(dst, b, h) do { _Pragma("unroll") for (int m = 0; m < 4; ++m) _Pragma("unroll") for (int k = 0; k < 2; ++k) dst[m][k] = *(const PG8_LAS bf16x8*)(lds + PG8_SA(b, h) + aoff + m * 2048 + k * 1024); } while (0)
; #define PG8_MMA(ai, bj, At, Bt) do { __builtin_amdgcn_s_setprio(1); _Pragma("unroll") for (int m = 0; m < 4; ++m) _Pragma("unroll") for (int n = 0; n < 2; ++n) _Pragma("unroll") for (int k = 0; k < 2; ++k) \
;         acc[ai][bj][m][n] = __builtin_amdgcn_mfma_f32_16x16x32_bf16(Bt[n][k], At[m][k], acc[ai][bj][m][n], 0, 0, 0); __builtin_amdgcn_s_setprio(0); } while (0)
; #define PG8_WAIT_V(n) asm volatile("s_waitcnt vmcnt(" #n ")" ::: "memory")
; #define PG8_WAIT_L(n) asm volatile("s_waitcnt lgkmcnt(" #n ")" ::: "memory")
; #define PG8_BAR __builtin_amdgcn_s_barrier()
; #define PG8_SCHED __builtin_amdgcn_sched_barrier(0)
; template <class Epi, class Sched, bool ALIGN_EPI = false, bool SP2 = false>
; __device__ __forceinline__ void gemm_phase(PG8_LAS unsigned char* lds, const Gemm g, const Sched& S, const Epi& E, int tid_in) {
;     ...
;             PG8_WAIT_V(8); PG8_WAIT_L(0); PG8_BAR; PG8_MMA(0, 0, At, B0); PG8_MMA(0, 1, At, B1); PG8_BAR; PG8_SCHED;
;             PG8_LDA(At, 1, 1); PG8_STAGE(PG8_SB(1, 0), b3, voffB); PG8_STAGE(PG8_SB(1, 1), b3 + hstep, voffB); PG8_STAGE(PG8_SA(1, 0), a3, voffA);
;             PG8_WAIT_V(8); PG8_WAIT_L(0); PG8_BAR; PG8_MMA(1, 0, At, B0); PG8_MMA(1, 1, At, B1); PG8_BAR; PG8_SCHED;
;     ...
;         if constexpr (ALIGN_EPI) { if (wr == 0) PG8_BAR; }
	v_mfma_f32_16x16x32_bf16 v[82:85], v[170:173], v[232:235], v[82:85]
	s_setprio 0
	s_mov_b32 m0, s67
	v_lshl_add_u64 v[174:175], v[174:175], 0, s[48:49]
	s_add_u32 s58, s86, 0x40080
	ds_read_b128 v[182:185], v177 offset:49152
	ds_read_b128 v[200:203], v177 offset:50176
	ds_read_b128 v[204:207], v177 offset:51200
	ds_read_b128 v[208:211], v177 offset:52224
	ds_read_b128 v[212:215], v177 offset:53248
	ds_read_b128 v[216:219], v177 offset:54272
	ds_read_b128 v[226:229], v177 offset:55296
	ds_read_b128 v[232:235], v177 offset:56320
	global_load_lds_dwordx4 v[174:175], off
	v_lshl_add_u64 v[174:175], v[178:179], 0, s[48:49]
	s_mov_b32 m0, s91
	s_addc_u32 s59, s87, 0
	global_load_lds_dwordx4 v[174:175], off
	v_lshl_add_u64 v[174:175], s[58:59], 0, v[148:149]
	s_mov_b32 m0, s75
	s_nop 0
	global_load_lds_dwordx4 v[174:175], off
	v_lshl_add_u64 v[174:175], s[58:59], 0, v[152:153]
	s_mov_b32 m0, s74
	s_nop 0
	global_load_lds_dwordx4 v[174:175], off
	v_lshl_add_u64 v[174:175], v[180:181], 0, s[48:49]
	s_mov_b32 m0, s53
	s_nop 0
	global_load_lds_dwordx4 v[174:175], off
	v_lshl_add_u64 v[174:175], v[236:237], 0, s[48:49]
	s_mov_b32 m0, s66
	s_nop 0
	global_load_lds_dwordx4 v[174:175], off
	s_waitcnt vmcnt(8)
	s_waitcnt lgkmcnt(0)
	s_barrier
	s_setprio 1
	s_waitcnt lgkmcnt(0)
	v_mfma_f32_16x16x32_bf16 v[76:79], v[48:51], v[182:185], v[76:79]
	v_mfma_f32_16x16x32_bf16 v[72:75], v[64:67], v[182:185], v[72:75]
	v_mfma_f32_16x16x32_bf16 v[60:63], v[48:51], v[204:207], v[60:63]
	v_mfma_f32_16x16x32_bf16 v[56:59], v[64:67], v[204:207], v[56:59]
	v_mfma_f32_16x16x32_bf16 v[28:31], v[48:51], v[212:215], v[28:31]
	v_mfma_f32_16x16x32_bf16 v[24:27], v[64:67], v[212:215], v[24:27]
	v_mfma_f32_16x16x32_bf16 v[12:15], v[48:51], v[226:229], v[12:15]
	v_mfma_f32_16x16x32_bf16 v[8:11], v[64:67], v[226:229], v[8:11]
	v_mfma_f32_16x16x32_bf16 v[76:79], v[52:55], v[200:203], v[76:79]
	v_mfma_f32_16x16x32_bf16 v[72:75], v[68:71], v[200:203], v[72:75]
	v_mfma_f32_16x16x32_bf16 v[60:63], v[52:55], v[208:211], v[60:63]
	v_mfma_f32_16x16x32_bf16 v[56:59], v[68:71], v[208:211], v[56:59]
	v_mfma_f32_16x16x32_bf16 v[28:31], v[52:55], v[216:219], v[28:31]
	v_mfma_f32_16x16x32_bf16 v[24:27], v[68:71], v[216:219], v[24:27]
	v_mfma_f32_16x16x32_bf16 v[12:15], v[52:55], v[232:235], v[12:15]
	v_mfma_f32_16x16x32_bf16 v[8:11], v[68:71], v[232:235], v[8:11]
	s_setprio 0
	s_setprio 1
	v_mfma_f32_16x16x32_bf16 v[32:35], v[158:161], v[182:185], v[32:35]
	v_mfma_f32_16x16x32_bf16 v[68:71], v[162:165], v[200:203], v[32:35]
	v_mfma_f32_16x16x32_bf16 v[32:35], v[166:169], v[182:185], v[36:39]
	v_mfma_f32_16x16x32_bf16 v[64:67], v[170:173], v[200:203], v[32:35]
	v_mfma_f32_16x16x32_bf16 v[32:35], v[158:161], v[204:207], v[44:47]
	v_mfma_f32_16x16x32_bf16 v[52:55], v[162:165], v[208:211], v[32:35]
	v_mfma_f32_16x16x32_bf16 v[32:35], v[166:169], v[204:207], v[40:43]
	v_mfma_f32_16x16x32_bf16 v[20:23], v[158:161], v[212:215], v[20:23]
	v_mfma_f32_16x16x32_bf16 v[16:19], v[166:169], v[212:215], v[16:19]
	v_mfma_f32_16x16x32_bf16 v[4:7], v[158:161], v[226:229], v[4:7]
	v_mfma_f32_16x16x32_bf16 v[0:3], v[166:169], v[226:229], v[0:3]
	v_mfma_f32_16x16x32_bf16 v[40:43], v[170:173], v[208:211], v[32:35]
	v_mfma_f32_16x16x32_bf16 v[20:23], v[162:165], v[216:219], v[20:23]
	v_mfma_f32_16x16x32_bf16 v[16:19], v[170:173], v[216:219], v[16:19]
	v_mfma_f32_16x16x32_bf16 v[4:7], v[162:165], v[232:235], v[4:7]
	s_barrier
	v_mfma_f32_16x16x32_bf16 v[0:3], v[170:173], v[232:235], v[0:3]
	s_setprio 0
	s_add_i32 s27, s27, 2
	s_add_u32 s84, s84, 0x100
	s_addc_u32 s85, s85, 0
	s_add_u32 s25, s25, 0x100
	s_addc_u32 s26, s26, 0
	s_cmp_gt_u32 s27, 13
	s_cbranch_scc0 .LBB0_158
	v_readlane_b32 s22, v254, 30
	v_readlane_b32 s23, v254, 31
	s_and_b64 vcc, exec, s[22:23]
	s_cbranch_vccz .LBB0_161
	s_barrier

; #define PG8_STAGE(bufoff, gbase, voff) do { _Pragma("unroll") for (int _i = 0; _i < 2; ++_i) \
;         __builtin_amdgcn_global_load_lds((const unsigned*)((const char*)(gbase) + (voff)[_i]), (PG8_LAS unsigned*)(lds + (bufoff) + ldsw + _i * 8192), 16, 0, 0); } while (0)
; #define PG8_LDA(dst, b, h) do { _Pragma("unroll") for (int m = 0; m < 4; ++m) _Pragma("unroll") for (int k = 0; k < 2; ++k) dst[m][k] = *(const PG8_LAS bf16x8*)(lds + PG8_SA(b, h) + aoff + m * 2048 + k * 1024); } while (0)
; #define PG8_LDB(dst, b, h) do { _Pragma("unroll") for (int n = 0; n < 2; ++n) _Pragma("unroll") for (int k = 0; k < 2; ++k) dst[n][k] = *(const PG8_LAS bf16x8*)(lds + PG8_SB(b, h) + boff + n * 2048 + k * 1024); } while (0)
; #define PG8_MMA(ai, bj, At, Bt) do { __builtin_amdgcn_s_setprio(1); _Pragma("unroll") for (int m = 0; m < 4; ++m) _Pragma("unroll") for (int n = 0; n < 2; ++n) _Pragma("unroll") for (int k = 0; k < 2; ++k) \
;         acc[ai][bj][m][n] = __builtin_amdgcn_mfma_f32_16x16x32_bf16(Bt[n][k], At[m][k], acc[ai][bj][m][n], 0, 0, 0); __builtin_amdgcn_s_setprio(0); } while (0)
; #define PG8_WAIT_V(n) asm volatile("s_waitcnt vmcnt(" #n ")" ::: "memory")
; #define PG8_WAIT_L(n) asm volatile("s_waitcnt lgkmcnt(" #n ")" ::: "memory")
; #define PG8_BAR __builtin_amdgcn_s_barrier()
; #define PG8_SCHED __builtin_amdgcn_sched_barrier(0)
; template <class Epi, class Sched, bool ALIGN_EPI = false, bool SP2 = false>
; __device__ __forceinline__ void gemm_phase(PG8_LAS unsigned char* lds, const Gemm g, const Sched& S, const Epi& E, int tid_in) {
;     ...
;             PG8_LDB(B0, 0, 0); PG8_LDB(B1, 0, 1); PG8_SCHED; PG8_LDA(At, 0, 0); PG8_STAGE(PG8_SA(1, 1), a1 + hstep, voffA);
;             PG8_WAIT_V(8); PG8_WAIT_L(0); PG8_BAR; PG8_MMA(0, 0, At, B0); PG8_MMA(0, 1, At, B1); PG8_BAR; PG8_SCHED;
;             PG8_LDA(At, 0, 1); PG8_STAGE(PG8_SB(0, 0), b2, voffB); PG8_STAGE(PG8_SB(0, 1), b2 + hstep, voffB); PG8_STAGE(PG8_SA(0, 0), a2, voffA);
;             PG8_WAIT_V(8); PG8_WAIT_L(0); PG8_BAR; PG8_MMA(1, 0, At, B0); PG8_MMA(1, 1, At, B1); PG8_BAR; PG8_SCHED;
.LBB0_440:
	v_or_b32_e32 v130, 0x10000, v248
	v_add_u32_e32 v134, 0x10400, v248
	v_add_u32_e32 v138, 0x10800, v248
	v_add_u32_e32 v142, 0x10c00, v248
	v_or_b32_e32 v146, 0x14000, v248
	v_add_u32_e32 v150, 0x14400, v248
	v_add_u32_e32 v154, 0x14800, v248
	v_add_u32_e32 v158, 0x14c00, v248
	ds_read_b128 v[130:133], v130
	ds_read_b128 v[134:137], v134
	ds_read_b128 v[138:141], v138
	ds_read_b128 v[142:145], v142
	ds_read_b128 v[146:149], v146
	ds_read_b128 v[150:153], v150
	ds_read_b128 v[154:157], v154
	ds_read_b128 v[158:161], v158
	s_add_u32 s80, s78, 0xfffc0080
	s_addc_u32 s81, s79, -1
	s_cmp_eq_u32 s87, 12
	s_cselect_b32 s83, s71, s81
	s_cselect_b32 s82, s77, s80
	s_cselect_b32 s81, s67, s86
	s_cselect_b32 s80, s84, s85
	v_lshl_add_u64 v[178:179], s[78:79], 0, v[202:203]
	s_add_i32 m0, s57, 0xc000
	ds_read_b128 v[162:165], v247
	ds_read_b128 v[166:169], v247 offset:1024
	ds_read_b128 v[170:173], v247 offset:2048
	ds_read_b128 v[174:177], v247 offset:3072
	ds_read_b128 v[182:185], v247 offset:4096
	ds_read_b128 v[212:215], v247 offset:5120
	ds_read_b128 v[226:229], v247 offset:6144
	ds_read_b128 v[232:235], v247 offset:7168
	global_load_lds_dwordx4 v[178:179], off
	v_lshl_add_u64 v[178:179], s[78:79], 0, v[204:205]
	s_add_i32 m0, s57, 0xe000
	s_nop 0
	global_load_lds_dwordx4 v[178:179], off
	s_waitcnt vmcnt(8)
	s_waitcnt lgkmcnt(0)
	s_barrier
	s_setprio 1
	s_waitcnt lgkmcnt(0)
	v_mfma_f32_16x16x32_bf16 v[126:129], v[130:133], v[162:165], v[126:129]
	v_mfma_f32_16x16x32_bf16 v[122:125], v[138:141], v[162:165], v[122:125]
	v_mfma_f32_16x16x32_bf16 v[114:117], v[130:133], v[170:173], v[114:117]
	v_mfma_f32_16x16x32_bf16 v[106:109], v[138:141], v[170:173], v[106:109]
	v_mfma_f32_16x16x32_bf16 v[98:101], v[130:133], v[182:185], v[98:101]
	v_mfma_f32_16x16x32_bf16 v[90:93], v[138:141], v[182:185], v[90:93]
	v_mfma_f32_16x16x32_bf16 v[76:79], v[130:133], v[226:229], v[76:79]
	v_mfma_f32_16x16x32_bf16 v[72:75], v[138:141], v[226:229], v[72:75]
	v_mfma_f32_16x16x32_bf16 v[126:129], v[134:137], v[166:169], v[126:129]
	v_mfma_f32_16x16x32_bf16 v[122:125], v[142:145], v[166:169], v[122:125]
	v_mfma_f32_16x16x32_bf16 v[114:117], v[134:137], v[174:177], v[114:117]
	v_mfma_f32_16x16x32_bf16 v[106:109], v[142:145], v[174:177], v[106:109]
	v_mfma_f32_16x16x32_bf16 v[98:101], v[134:137], v[212:215], v[98:101]
	v_mfma_f32_16x16x32_bf16 v[90:93], v[142:145], v[212:215], v[90:93]
	v_mfma_f32_16x16x32_bf16 v[76:79], v[134:137], v[232:235], v[76:79]
	v_mfma_f32_16x16x32_bf16 v[72:75], v[142:145], v[232:235], v[72:75]
	s_setprio 0
	s_setprio 1
	v_mfma_f32_16x16x32_bf16 v[118:121], v[146:149], v[162:165], v[118:121]
	v_mfma_f32_16x16x32_bf16 v[110:113], v[154:157], v[162:165], v[110:113]
	v_mfma_f32_16x16x32_bf16 v[102:105], v[146:149], v[170:173], v[102:105]
	v_mfma_f32_16x16x32_bf16 v[94:97], v[154:157], v[170:173], v[94:97]
	v_mfma_f32_16x16x32_bf16 v[86:89], v[146:149], v[182:185], v[86:89]
	v_mfma_f32_16x16x32_bf16 v[82:85], v[154:157], v[182:185], v[82:85]
	v_mfma_f32_16x16x32_bf16 v[68:71], v[146:149], v[226:229], v[68:71]
	v_mfma_f32_16x16x32_bf16 v[64:67], v[154:157], v[226:229], v[64:67]
	v_mfma_f32_16x16x32_bf16 v[118:121], v[150:153], v[166:169], v[118:121]
	v_mfma_f32_16x16x32_bf16 v[110:113], v[158:161], v[166:169], v[110:113]
	v_mfma_f32_16x16x32_bf16 v[102:105], v[150:153], v[174:177], v[102:105]
	v_mfma_f32_16x16x32_bf16 v[94:97], v[158:161], v[174:177], v[94:97]
	v_mfma_f32_16x16x32_bf16 v[86:89], v[150:153], v[212:215], v[86:89]
	v_mfma_f32_16x16x32_bf16 v[82:85], v[158:161], v[212:215], v[82:85]
	v_mfma_f32_16x16x32_bf16 v[68:71], v[150:153], v[232:235], v[68:71]
	s_barrier
	v_mfma_f32_16x16x32_bf16 v[64:67], v[158:161], v[232:235], v[64:67]
	s_setprio 0
	s_mov_b32 m0, s20
	v_lshl_add_u64 v[178:179], s[80:81], 0, v[198:199]
	s_add_u32 s88, s80, 0x40000
	ds_read_b128 v[162:165], v247 offset:16384
	ds_read_b128 v[166:169], v247 offset:17408
	ds_read_b128 v[170:173], v247 offset:18432
	ds_read_b128 v[174:177], v247 offset:19456
	ds_read_b128 v[182:185], v247 offset:20480
	ds_read_b128 v[212:215], v247 offset:21504
	ds_read_b128 v[226:229], v247 offset:22528
	ds_read_b128 v[232:235], v247 offset:23552
	global_load_lds_dwordx4 v[178:179], off
	v_lshl_add_u64 v[180:181], s[80:81], 0, v[194:195]
	s_mov_b32 m0, s21
	s_addc_u32 s89, s81, 0
	global_load_lds_dwordx4 v[180:181], off
	v_lshl_add_u64 v[208:209], s[88:89], 0, v[198:199]
	s_mov_b32 m0, s22
	v_lshl_add_u64 v[218:219], s[82:83], 0, v[196:197]
	global_load_lds_dwordx4 v[208:209], off
	v_lshl_add_u64 v[208:209], s[88:89], 0, v[194:195]
	s_mov_b32 m0, s23
	s_nop 0
	global_load_lds_dwordx4 v[208:209], off
	v_lshl_add_u64 v[208:209], s[82:83], 0, v[200:201]
	s_mov_b32 m0, s57
	s_nop 0
	global_load_lds_dwordx4 v[208:209], off
	s_mov_b32 m0, s24
	s_nop 0
	global_load_lds_dwordx4 v[218:219], off
	s_waitcnt vmcnt(8)
	s_waitcnt lgkmcnt(0)
	s_barrier
; #define PG8_STAGE(bufoff, gbase, voff) do { _Pragma("unroll") for (int _i = 0; _i < 2; ++_i) \
;         __builtin_amdgcn_global_load_lds((const unsigned*)((const char*)(gbase) + (voff)[_i]), (PG8_LAS unsigned*)(lds + (bufoff) + ldsw + _i * 8192), 16, 0, 0); } while (0)
; #define PG8_LDA(dst, b, h) do { _Pragma("unroll") for (int m = 0; m < 4; ++m) _Pragma("unroll") for (int k = 0; k < 2; ++k) dst[m][k] = *(const PG8_LAS bf16x8*)(lds + PG8_SA(b, h) + aoff + m * 2048 + k * 1024); } while (0)
; #define PG8_LDB(dst, b, h) do { _Pragma("unroll") for (int n = 0; n < 2; ++n) _Pragma("unroll") for (int k = 0; k < 2; ++k) dst[n][k] = *(const PG8_LAS bf16x8*)(lds + PG8_SB(b, h) + boff + n * 2048 + k * 1024); } while (0)
; #define PG8_MMA(ai, bj, At, Bt) do { __builtin_amdgcn_s_setprio(1); _Pragma("unroll") for (int m = 0; m < 4; ++m) _Pragma("unroll") for (int n = 0; n < 2; ++n) _Pragma("unroll") for (int k = 0; k < 2; ++k) \
;         acc[ai][bj][m][n] = __builtin_amdgcn_mfma_f32_16x16x32_bf16(Bt[n][k], At[m][k], acc[ai][bj][m][n], 0, 0, 0); __builtin_amdgcn_s_setprio(0); } while (0)
; #define PG8_WAIT_V(n) asm volatile("s_waitcnt vmcnt(" #n ")" ::: "memory")
; #define PG8_WAIT_L(n) asm volatile("s_waitcnt lgkmcnt(" #n ")" ::: "memory")
; #define PG8_BAR __builtin_amdgcn_s_barrier()
; #define PG8_SCHED __builtin_amdgcn_sched_barrier(0)
; template <class Epi, class Sched, bool ALIGN_EPI = false, bool SP2 = false>
; __device__ __forceinline__ void gemm_phase(PG8_LAS unsigned char* lds, const Gemm g, const Sched& S, const Epi& E, int tid_in) {
;     ...
;             PG8_WAIT_V(8); PG8_WAIT_L(0); PG8_BAR; PG8_MMA(1, 0, At, B0); PG8_MMA(1, 1, At, B1); PG8_BAR; PG8_SCHED;
;             PG8_LDB(B0, 1, 0); PG8_LDB(B1, 1, 1); PG8_SCHED; PG8_LDA(At, 1, 0); PG8_STAGE(PG8_SA(0, 1), a2 + hstep, voffA);
;             PG8_WAIT_V(8); PG8_WAIT_L(0); PG8_BAR; PG8_MMA(0, 0, At, B0); PG8_MMA(0, 1, At, B1); PG8_BAR; PG8_SCHED;
	s_setprio 1
	s_waitcnt lgkmcnt(0)
	v_mfma_f32_16x16x32_bf16 v[60:63], v[130:133], v[162:165], v[60:63]
	v_mfma_f32_16x16x32_bf16 v[56:59], v[138:141], v[162:165], v[56:59]
	v_mfma_f32_16x16x32_bf16 v[44:47], v[130:133], v[170:173], v[44:47]
	v_mfma_f32_16x16x32_bf16 v[40:43], v[138:141], v[170:173], v[40:43]
	v_mfma_f32_16x16x32_bf16 v[28:31], v[130:133], v[182:185], v[28:31]
	v_mfma_f32_16x16x32_bf16 v[24:27], v[138:141], v[182:185], v[24:27]
	v_mfma_f32_16x16x32_bf16 v[12:15], v[130:133], v[226:229], v[12:15]
	v_mfma_f32_16x16x32_bf16 v[8:11], v[138:141], v[226:229], v[8:11]
	v_mfma_f32_16x16x32_bf16 v[60:63], v[134:137], v[166:169], v[60:63]
	v_mfma_f32_16x16x32_bf16 v[56:59], v[142:145], v[166:169], v[56:59]
	v_mfma_f32_16x16x32_bf16 v[44:47], v[134:137], v[174:177], v[44:47]
	v_mfma_f32_16x16x32_bf16 v[40:43], v[142:145], v[174:177], v[40:43]
	v_mfma_f32_16x16x32_bf16 v[28:31], v[134:137], v[212:215], v[28:31]
	v_mfma_f32_16x16x32_bf16 v[24:27], v[142:145], v[212:215], v[24:27]
	v_mfma_f32_16x16x32_bf16 v[12:15], v[134:137], v[232:235], v[12:15]
	v_mfma_f32_16x16x32_bf16 v[8:11], v[142:145], v[232:235], v[8:11]
	s_setprio 0
	s_setprio 1
	v_mfma_f32_16x16x32_bf16 v[52:55], v[146:149], v[162:165], v[52:55]
	v_mfma_f32_16x16x32_bf16 v[48:51], v[154:157], v[162:165], v[48:51]
	v_mfma_f32_16x16x32_bf16 v[36:39], v[146:149], v[170:173], v[36:39]
	v_mfma_f32_16x16x32_bf16 v[32:35], v[154:157], v[170:173], v[32:35]
	v_mfma_f32_16x16x32_bf16 v[20:23], v[146:149], v[182:185], v[20:23]
	v_mfma_f32_16x16x32_bf16 v[16:19], v[154:157], v[182:185], v[16:19]
	v_mfma_f32_16x16x32_bf16 v[4:7], v[146:149], v[226:229], v[4:7]
	v_mfma_f32_16x16x32_bf16 v[0:3], v[154:157], v[226:229], v[0:3]
	v_mfma_f32_16x16x32_bf16 v[52:55], v[150:153], v[166:169], v[52:55]
	v_mfma_f32_16x16x32_bf16 v[48:51], v[158:161], v[166:169], v[48:51]
	v_mfma_f32_16x16x32_bf16 v[36:39], v[150:153], v[174:177], v[36:39]
	v_mfma_f32_16x16x32_bf16 v[32:35], v[158:161], v[174:177], v[32:35]
	v_mfma_f32_16x16x32_bf16 v[20:23], v[150:153], v[212:215], v[20:23]
	v_mfma_f32_16x16x32_bf16 v[16:19], v[158:161], v[212:215], v[16:19]
	v_mfma_f32_16x16x32_bf16 v[4:7], v[150:153], v[232:235], v[4:7]
	s_barrier
	v_mfma_f32_16x16x32_bf16 v[0:3], v[158:161], v[232:235], v[0:3]
	s_setprio 0
	v_or_b32_e32 v130, 0x18000, v248
	v_add_u32_e32 v134, 0x18400, v248
	v_add_u32_e32 v138, 0x18800, v248
	v_add_u32_e32 v142, 0x18c00, v248
	v_or_b32_e32 v146, 0x1c000, v248
	v_add_u32_e32 v150, 0x1c400, v248
	v_add_u32_e32 v154, 0x1c800, v248
	v_add_u32_e32 v158, 0x1cc00, v248
	ds_read_b128 v[130:133], v130
	ds_read_b128 v[134:137], v134
	ds_read_b128 v[138:141], v138
	ds_read_b128 v[142:145], v142
	ds_read_b128 v[146:149], v146
	ds_read_b128 v[150:153], v150
	ds_read_b128 v[154:157], v154
	ds_read_b128 v[158:161], v158
	s_add_u32 s82, s82, 0x40000
	s_addc_u32 s83, s83, 0
	s_mov_b32 m0, s25
	v_lshl_add_u64 v[236:237], s[82:83], 0, v[200:201]
	ds_read_b128 v[162:165], v247 offset:32768
	ds_read_b128 v[166:169], v247 offset:33792
	ds_read_b128 v[170:173], v247 offset:34816
	ds_read_b128 v[174:177], v247 offset:35840
	ds_read_b128 v[182:185], v247 offset:36864
	ds_read_b128 v[212:215], v247 offset:37888
	ds_read_b128 v[226:229], v247 offset:38912
	ds_read_b128 v[232:235], v247 offset:39936
	global_load_lds_dwordx4 v[236:237], off
	v_lshl_add_u64 v[236:237], s[82:83], 0, v[196:197]
	s_mov_b32 m0, s26
	s_nop 0
	global_load_lds_dwordx4 v[236:237], off
	s_waitcnt vmcnt(8)
	s_waitcnt lgkmcnt(0)
	s_barrier
	s_setprio 1
	s_waitcnt lgkmcnt(0)
	v_mfma_f32_16x16x32_bf16 v[126:129], v[130:133], v[162:165], v[126:129]
	v_mfma_f32_16x16x32_bf16 v[122:125], v[138:141], v[162:165], v[122:125]
	v_mfma_f32_16x16x32_bf16 v[114:117], v[130:133], v[170:173], v[114:117]
	v_mfma_f32_16x16x32_bf16 v[106:109], v[138:141], v[170:173], v[106:109]
	v_mfma_f32_16x16x32_bf16 v[98:101], v[130:133], v[182:185], v[98:101]
	v_mfma_f32_16x16x32_bf16 v[90:93], v[138:141], v[182:185], v[90:93]
	v_mfma_f32_16x16x32_bf16 v[76:79], v[130:133], v[226:229], v[76:79]
	v_mfma_f32_16x16x32_bf16 v[72:75], v[138:141], v[226:229], v[72:75]
	v_mfma_f32_16x16x32_bf16 v[126:129], v[134:137], v[166:169], v[126:129]
	v_mfma_f32_16x16x32_bf16 v[122:125], v[142:145], v[166:169], v[122:125]
	v_mfma_f32_16x16x32_bf16 v[114:117], v[134:137], v[174:177], v[114:117]
	v_mfma_f32_16x16x32_bf16 v[106:109], v[142:145], v[174:177], v[106:109]
	v_mfma_f32_16x16x32_bf16 v[98:101], v[134:137], v[212:215], v[98:101]
	v_mfma_f32_16x16x32_bf16 v[90:93], v[142:145], v[212:215], v[90:93]
	v_mfma_f32_16x16x32_bf16 v[76:79], v[134:137], v[232:235], v[76:79]
	v_mfma_f32_16x16x32_bf16 v[72:75], v[142:145], v[232:235], v[72:75]
	s_setprio 0
	s_setprio 1
	v_mfma_f32_16x16x32_bf16 v[118:121], v[146:149], v[162:165], v[118:121]
	v_mfma_f32_16x16x32_bf16 v[110:113], v[154:157], v[162:165], v[110:113]
	v_mfma_f32_16x16x32_bf16 v[102:105], v[146:149], v[170:173], v[102:105]
	v_mfma_f32_16x16x32_bf16 v[94:97], v[154:157], v[170:173], v[94:97]
	v_mfma_f32_16x16x32_bf16 v[86:89], v[146:149], v[182:185], v[86:89]
	v_mfma_f32_16x16x32_bf16 v[82:85], v[154:157], v[182:185], v[82:85]
	v_mfma_f32_16x16x32_bf16 v[68:71], v[146:149], v[226:229], v[68:71]
	v_mfma_f32_16x16x32_bf16 v[64:67], v[154:157], v[226:229], v[64:67]
	v_mfma_f32_16x16x32_bf16 v[118:121], v[150:153], v[166:169], v[118:121]
	v_mfma_f32_16x16x32_bf16 v[110:113], v[158:161], v[166:169], v[110:113]
	v_mfma_f32_16x16x32_bf16 v[102:105], v[150:153], v[174:177], v[102:105]
	v_mfma_f32_16x16x32_bf16 v[94:97], v[158:161], v[174:177], v[94:97]
	v_mfma_f32_16x16x32_bf16 v[86:89], v[150:153], v[212:215], v[86:89]
	v_mfma_f32_16x16x32_bf16 v[82:85], v[158:161], v[212:215], v[82:85]
	v_mfma_f32_16x16x32_bf16 v[68:71], v[150:153], v[232:235], v[68:71]
	s_barrier
; #define PG8_STAGE(bufoff, gbase, voff) do { _Pragma("unroll") for (int _i = 0; _i < 2; ++_i) \
;         __builtin_amdgcn_global_load_lds((const unsigned*)((const char*)(gbase) + (voff)[_i]), (PG8_LAS unsigned*)(lds + (bufoff) + ldsw + _i * 8192), 16, 0, 0); } while (0)
; #define PG8_LDA(dst, b, h) do { _Pragma("unroll") for (int m = 0; m < 4; ++m) _Pragma("unroll") for (int k = 0; k < 2; ++k) dst[m][k] = *(const PG8_LAS bf16x8*)(lds + PG8_SA(b, h) + aoff + m * 2048 + k * 1024); } while (0)
; #define PG8_MMA(ai, bj, At, Bt) do { __builtin_amdgcn_s_setprio(1); _Pragma("unroll") for (int m = 0; m < 4; ++m) _Pragma("unroll") for (int n = 0; n < 2; ++n) _Pragma("unroll") for (int k = 0; k < 2; ++k) \
;         acc[ai][bj][m][n] = __builtin_amdgcn_mfma_f32_16x16x32_bf16(Bt[n][k], At[m][k], acc[ai][bj][m][n], 0, 0, 0); __builtin_amdgcn_s_setprio(0); } while (0)
; #define PG8_WAIT_V(n) asm volatile("s_waitcnt vmcnt(" #n ")" ::: "memory")
; #define PG8_WAIT_L(n) asm volatile("s_waitcnt lgkmcnt(" #n ")" ::: "memory")
; #define PG8_BAR __builtin_amdgcn_s_barrier()
; #define PG8_SCHED __builtin_amdgcn_sched_barrier(0)
; template <class Epi, class Sched, bool ALIGN_EPI = false, bool SP2 = false>
; __device__ __forceinline__ void gemm_phase(PG8_LAS unsigned char* lds, const Gemm g, const Sched& S, const Epi& E, int tid_in) {
;     ...
;             PG8_WAIT_V(8); PG8_WAIT_L(0); PG8_BAR; PG8_MMA(0, 0, At, B0); PG8_MMA(0, 1, At, B1); PG8_BAR; PG8_SCHED;
;             PG8_LDA(At, 1, 1); PG8_STAGE(PG8_SB(1, 0), b3, voffB); PG8_STAGE(PG8_SB(1, 1), b3 + hstep, voffB); PG8_STAGE(PG8_SA(1, 0), a3, voffA);
;             PG8_WAIT_V(8); PG8_WAIT_L(0); PG8_BAR; PG8_MMA(1, 0, At, B0); PG8_MMA(1, 1, At, B1); PG8_BAR; PG8_SCHED;
;     ...
;         if constexpr (ALIGN_EPI) { if (wr == 0) PG8_BAR; }
	v_mfma_f32_16x16x32_bf16 v[64:67], v[158:161], v[232:235], v[64:67]
	s_setprio 0
	s_mov_b32 m0, s27
	v_lshl_add_u64 v[178:179], v[178:179], 0, s[48:49]
	s_add_u32 s80, s80, 0x40080
	ds_read_b128 v[162:165], v247 offset:49152
	ds_read_b128 v[166:169], v247 offset:50176
	ds_read_b128 v[170:173], v247 offset:51200
	ds_read_b128 v[174:177], v247 offset:52224
	ds_read_b128 v[182:185], v247 offset:53248
	ds_read_b128 v[212:215], v247 offset:54272
	ds_read_b128 v[226:229], v247 offset:55296
	ds_read_b128 v[232:235], v247 offset:56320
	global_load_lds_dwordx4 v[178:179], off
	v_lshl_add_u64 v[178:179], v[180:181], 0, s[48:49]
	s_mov_b32 m0, s58
	s_addc_u32 s81, s81, 0
	global_load_lds_dwordx4 v[178:179], off
	v_lshl_add_u64 v[178:179], s[80:81], 0, v[198:199]
	s_mov_b32 m0, s63
	s_nop 0
	global_load_lds_dwordx4 v[178:179], off
	v_lshl_add_u64 v[178:179], s[80:81], 0, v[194:195]
	s_mov_b32 m0, s64
	s_nop 0
	global_load_lds_dwordx4 v[178:179], off
	v_lshl_add_u64 v[178:179], v[208:209], 0, s[48:49]
	s_mov_b32 m0, s59
	s_nop 0
	global_load_lds_dwordx4 v[178:179], off
	v_lshl_add_u64 v[178:179], v[218:219], 0, s[48:49]
	s_mov_b32 m0, s62
	s_nop 0
	global_load_lds_dwordx4 v[178:179], off
	s_waitcnt vmcnt(8)
	s_waitcnt lgkmcnt(0)
	s_barrier
	s_setprio 1
	s_waitcnt lgkmcnt(0)
	v_mfma_f32_16x16x32_bf16 v[60:63], v[130:133], v[162:165], v[60:63]
	v_mfma_f32_16x16x32_bf16 v[56:59], v[138:141], v[162:165], v[56:59]
	v_mfma_f32_16x16x32_bf16 v[44:47], v[130:133], v[170:173], v[44:47]
	v_mfma_f32_16x16x32_bf16 v[40:43], v[138:141], v[170:173], v[40:43]
	v_mfma_f32_16x16x32_bf16 v[28:31], v[130:133], v[182:185], v[28:31]
	v_mfma_f32_16x16x32_bf16 v[24:27], v[138:141], v[182:185], v[24:27]
	v_mfma_f32_16x16x32_bf16 v[12:15], v[130:133], v[226:229], v[12:15]
	v_mfma_f32_16x16x32_bf16 v[8:11], v[138:141], v[226:229], v[8:11]
	v_mfma_f32_16x16x32_bf16 v[60:63], v[134:137], v[166:169], v[60:63]
	v_mfma_f32_16x16x32_bf16 v[56:59], v[142:145], v[166:169], v[56:59]
	v_mfma_f32_16x16x32_bf16 v[44:47], v[134:137], v[174:177], v[44:47]
	v_mfma_f32_16x16x32_bf16 v[40:43], v[142:145], v[174:177], v[40:43]
	v_mfma_f32_16x16x32_bf16 v[28:31], v[134:137], v[212:215], v[28:31]
	v_mfma_f32_16x16x32_bf16 v[24:27], v[142:145], v[212:215], v[24:27]
	v_mfma_f32_16x16x32_bf16 v[12:15], v[134:137], v[232:235], v[12:15]
	v_mfma_f32_16x16x32_bf16 v[8:11], v[142:145], v[232:235], v[8:11]
	s_setprio 0
	s_setprio 1
	v_mfma_f32_16x16x32_bf16 v[52:55], v[146:149], v[162:165], v[52:55]
	v_mfma_f32_16x16x32_bf16 v[48:51], v[154:157], v[162:165], v[48:51]
	v_mfma_f32_16x16x32_bf16 v[36:39], v[146:149], v[170:173], v[36:39]
	v_mfma_f32_16x16x32_bf16 v[32:35], v[154:157], v[170:173], v[32:35]
	v_mfma_f32_16x16x32_bf16 v[20:23], v[146:149], v[182:185], v[20:23]
	v_mfma_f32_16x16x32_bf16 v[16:19], v[154:157], v[182:185], v[16:19]
	v_mfma_f32_16x16x32_bf16 v[4:7], v[146:149], v[226:229], v[4:7]
	v_mfma_f32_16x16x32_bf16 v[0:3], v[154:157], v[226:229], v[0:3]
	v_mfma_f32_16x16x32_bf16 v[52:55], v[150:153], v[166:169], v[52:55]
	v_mfma_f32_16x16x32_bf16 v[48:51], v[158:161], v[166:169], v[48:51]
	v_mfma_f32_16x16x32_bf16 v[36:39], v[150:153], v[174:177], v[36:39]
	v_mfma_f32_16x16x32_bf16 v[32:35], v[158:161], v[174:177], v[32:35]
	v_mfma_f32_16x16x32_bf16 v[20:23], v[150:153], v[212:215], v[20:23]
	v_mfma_f32_16x16x32_bf16 v[16:19], v[158:161], v[212:215], v[16:19]
	v_mfma_f32_16x16x32_bf16 v[4:7], v[150:153], v[232:235], v[4:7]
	s_barrier
	v_mfma_f32_16x16x32_bf16 v[0:3], v[158:161], v[232:235], v[0:3]
	s_setprio 0
	s_add_i32 s87, s87, 2
	s_add_u32 s78, s78, 0x100
	s_addc_u32 s79, s79, 0
	s_add_u32 s85, s85, 0x100
	s_addc_u32 s86, s86, 0
	s_cmp_gt_u32 s87, 13
	s_cbranch_scc0 .LBB0_440
	v_mov_b32_e32 v239, 0x60
	v_mov_b32_e32 v236, 0xc0
	s_and_b64 vcc, exec, s[42:43]
	s_cbranch_vccz .LBB0_443
	s_barrier

; #define PG8_STAGE(bufoff, gbase, voff) do { _Pragma("unroll") for (int _i = 0; _i < 2; ++_i) \
;         __builtin_amdgcn_global_load_lds((const unsigned*)((const char*)(gbase) + (voff)[_i]), (PG8_LAS unsigned*)(lds + (bufoff) + ldsw + _i * 8192), 16, 0, 0); } while (0)
; #define PG8_LDA(dst, b, h) do { _Pragma("unroll") for (int m = 0; m < 4; ++m) _Pragma("unroll") for (int k = 0; k < 2; ++k) dst[m][k] = *(const PG8_LAS bf16x8*)(lds + PG8_SA(b, h) + aoff + m * 2048 + k * 1024); } while (0)
; #define PG8_LDB(dst, b, h) do { _Pragma("unroll") for (int n = 0; n < 2; ++n) _Pragma("unroll") for (int k = 0; k < 2; ++k) dst[n][k] = *(const PG8_LAS bf16x8*)(lds + PG8_SB(b, h) + boff + n * 2048 + k * 1024); } while (0)
; #define PG8_MMA(ai, bj, At, Bt) do { __builtin_amdgcn_s_setprio(1); _Pragma("unroll") for (int m = 0; m < 4; ++m) _Pragma("unroll") for (int n = 0; n < 2; ++n) _Pragma("unroll") for (int k = 0; k < 2; ++k) \
;         acc[ai][bj][m][n] = __builtin_amdgcn_mfma_f32_16x16x32_bf16(Bt[n][k], At[m][k], acc[ai][bj][m][n], 0, 0, 0); __builtin_amdgcn_s_setprio(0); } while (0)
; #define PG8_WAIT_V(n) asm volatile("s_waitcnt vmcnt(" #n ")" ::: "memory")
; #define PG8_WAIT_L(n) asm volatile("s_waitcnt lgkmcnt(" #n ")" ::: "memory")
; #define PG8_BAR __builtin_amdgcn_s_barrier()
; #define PG8_SCHED __builtin_amdgcn_sched_barrier(0)
; template <class Epi, class Sched, bool ALIGN_EPI = false, bool SP2 = false>
; __device__ __forceinline__ void gemm_phase(PG8_LAS unsigned char* lds, const Gemm g, const Sched& S, const Epi& E, int tid_in) {
;     ...
;             PG8_LDB(B0, 0, 0); PG8_LDB(B1, 0, 1); PG8_SCHED; PG8_LDA(At, 0, 0); PG8_STAGE(PG8_SA(1, 1), a1 + hstep, voffA);
;             PG8_WAIT_V(8); PG8_WAIT_L(0); PG8_BAR; PG8_MMA(0, 0, At, B0); PG8_MMA(0, 1, At, B1); PG8_BAR; PG8_SCHED;
;             PG8_LDA(At, 0, 1); PG8_STAGE(PG8_SB(0, 0), b2, voffB); PG8_STAGE(PG8_SB(0, 1), b2 + hstep, voffB); PG8_STAGE(PG8_SA(0, 0), a2, voffA);
;             PG8_WAIT_V(8); PG8_WAIT_L(0); PG8_BAR; PG8_MMA(1, 0, At, B0); PG8_MMA(1, 1, At, B1); PG8_BAR; PG8_SCHED;
.LBB0_508:
	v_or_b32_e32 v40, 0x10000, v215
	v_add_u32_e32 v44, 0x10400, v215
	v_add_u32_e32 v52, 0x10800, v215
	v_add_u32_e32 v60, 0x10c00, v215
	v_or_b32_e32 v146, 0x14000, v215
	v_add_u32_e32 v150, 0x14400, v215
	v_add_u32_e32 v154, 0x14800, v215
	v_add_u32_e32 v158, 0x14c00, v215
	s_add_i32 s44, s42, 2
	ds_read_b128 v[40:43], v40
	ds_read_b128 v[44:47], v44
	ds_read_b128 v[52:55], v52
	ds_read_b128 v[60:63], v60
	ds_read_b128 v[146:149], v146
	ds_read_b128 v[150:153], v150
	ds_read_b128 v[154:157], v154
	ds_read_b128 v[158:161], v158
	s_add_u32 s45, s40, 0x80
	s_addc_u32 s43, s41, 0
	s_cmp_eq_u32 s94, s42
	s_cselect_b32 s42, s88, s45
	s_cselect_b32 s43, s89, s43
	s_cselect_b32 s93, s91, s27
	s_cselect_b32 s92, s90, s26
	v_lshl_add_u64 v[218:219], s[40:41], 0, v[174:175]
	s_add_i32 m0, s57, 0xc000
	ds_read_b128 v[194:197], v214
	ds_read_b128 v[198:201], v214 offset:1024
	ds_read_b128 v[202:205], v214 offset:2048
	ds_read_b128 v[206:209], v214 offset:3072
	ds_read_b128 v[210:213], v214 offset:4096
	ds_read_b128 v[226:229], v214 offset:5120
	ds_read_b128 v[232:235], v214 offset:6144
	ds_read_b128 v[182:185], v214 offset:7168
	global_load_lds_dwordx4 v[218:219], off
	v_lshl_add_u64 v[218:219], s[40:41], 0, v[176:177]
	s_add_i32 m0, s57, 0xe000
	s_nop 0
	global_load_lds_dwordx4 v[218:219], off
	s_waitcnt vmcnt(8)
	s_waitcnt lgkmcnt(0)
	s_barrier
	s_setprio 1
	s_waitcnt lgkmcnt(0)
	v_mfma_f32_16x16x32_bf16 v[142:145], v[40:43], v[194:197], v[142:145]
	v_mfma_f32_16x16x32_bf16 v[138:141], v[52:55], v[194:197], v[138:141]
	v_mfma_f32_16x16x32_bf16 v[126:129], v[40:43], v[202:205], v[126:129]
	v_mfma_f32_16x16x32_bf16 v[122:125], v[52:55], v[202:205], v[122:125]
	v_mfma_f32_16x16x32_bf16 v[110:113], v[40:43], v[210:213], v[110:113]
	v_mfma_f32_16x16x32_bf16 v[106:109], v[52:55], v[210:213], v[106:109]
	v_mfma_f32_16x16x32_bf16 v[94:97], v[40:43], v[232:235], v[94:97]
	v_mfma_f32_16x16x32_bf16 v[90:93], v[52:55], v[232:235], v[90:93]
	v_mfma_f32_16x16x32_bf16 v[142:145], v[44:47], v[198:201], v[142:145]
	v_mfma_f32_16x16x32_bf16 v[138:141], v[60:63], v[198:201], v[138:141]
	v_mfma_f32_16x16x32_bf16 v[126:129], v[44:47], v[206:209], v[126:129]
	v_mfma_f32_16x16x32_bf16 v[122:125], v[60:63], v[206:209], v[122:125]
	v_mfma_f32_16x16x32_bf16 v[110:113], v[44:47], v[226:229], v[110:113]
	v_mfma_f32_16x16x32_bf16 v[106:109], v[60:63], v[226:229], v[106:109]
	v_mfma_f32_16x16x32_bf16 v[94:97], v[44:47], v[182:185], v[94:97]
	v_mfma_f32_16x16x32_bf16 v[90:93], v[60:63], v[182:185], v[90:93]
	s_setprio 0
	s_setprio 1
	v_mfma_f32_16x16x32_bf16 v[134:137], v[146:149], v[194:197], v[134:137]
	v_mfma_f32_16x16x32_bf16 v[130:133], v[154:157], v[194:197], v[130:133]
	v_mfma_f32_16x16x32_bf16 v[118:121], v[146:149], v[202:205], v[118:121]
	v_mfma_f32_16x16x32_bf16 v[114:117], v[154:157], v[202:205], v[114:117]
	v_mfma_f32_16x16x32_bf16 v[102:105], v[146:149], v[210:213], v[102:105]
	v_mfma_f32_16x16x32_bf16 v[98:101], v[154:157], v[210:213], v[98:101]
	v_mfma_f32_16x16x32_bf16 v[86:89], v[146:149], v[232:235], v[86:89]
	v_mfma_f32_16x16x32_bf16 v[82:85], v[154:157], v[232:235], v[82:85]
	v_mfma_f32_16x16x32_bf16 v[134:137], v[150:153], v[198:201], v[134:137]
	v_mfma_f32_16x16x32_bf16 v[130:133], v[158:161], v[198:201], v[130:133]
	v_mfma_f32_16x16x32_bf16 v[118:121], v[150:153], v[206:209], v[118:121]
	v_mfma_f32_16x16x32_bf16 v[114:117], v[158:161], v[206:209], v[114:117]
	v_mfma_f32_16x16x32_bf16 v[102:105], v[150:153], v[226:229], v[102:105]
	v_mfma_f32_16x16x32_bf16 v[98:101], v[158:161], v[226:229], v[98:101]
	v_mfma_f32_16x16x32_bf16 v[86:89], v[150:153], v[182:185], v[86:89]
	s_barrier
	v_mfma_f32_16x16x32_bf16 v[82:85], v[158:161], v[182:185], v[82:85]
	s_setprio 0
	s_mov_b32 m0, s95
	v_lshl_add_u64 v[218:219], s[92:93], 0, v[164:165]
	v_lshl_add_u64 v[250:251], s[92:93], 0, v[168:169]
	s_add_u32 s92, s92, s70
	ds_read_b128 v[182:185], v214 offset:16384
	ds_read_b128 v[194:197], v214 offset:17408
	ds_read_b128 v[198:201], v214 offset:18432
	ds_read_b128 v[202:205], v214 offset:19456
	ds_read_b128 v[206:209], v214 offset:20480
	ds_read_b128 v[210:213], v214 offset:21504
	ds_read_b128 v[226:229], v214 offset:22528
	ds_read_b128 v[232:235], v214 offset:23552
	global_load_lds_dwordx4 v[218:219], off
	s_mov_b32 m0, s31
	s_addc_u32 s93, s93, 0
	global_load_lds_dwordx4 v[250:251], off
	v_lshl_add_u64 v[236:237], s[92:93], 0, v[164:165]
	s_mov_b32 m0, s68
	v_lshl_add_u64 v[238:239], s[92:93], 0, v[168:169]
	global_load_lds_dwordx4 v[236:237], off
	s_mov_b32 m0, s69
	v_lshl_add_u64 v[240:241], s[42:43], 0, v[162:163]
	global_load_lds_dwordx4 v[238:239], off
	s_mov_b32 m0, s57
	v_lshl_add_u64 v[178:179], s[42:43], 0, v[166:167]
	global_load_lds_dwordx4 v[240:241], off
	s_mov_b32 m0, s29
	s_nop 0
	global_load_lds_dwordx4 v[178:179], off
	s_waitcnt vmcnt(8)
	s_waitcnt lgkmcnt(0)
	s_barrier
; #define PG8_STAGE(bufoff, gbase, voff) do { _Pragma("unroll") for (int _i = 0; _i < 2; ++_i) \
;         __builtin_amdgcn_global_load_lds((const unsigned*)((const char*)(gbase) + (voff)[_i]), (PG8_LAS unsigned*)(lds + (bufoff) + ldsw + _i * 8192), 16, 0, 0); } while (0)
; #define PG8_LDA(dst, b, h) do { _Pragma("unroll") for (int m = 0; m < 4; ++m) _Pragma("unroll") for (int k = 0; k < 2; ++k) dst[m][k] = *(const PG8_LAS bf16x8*)(lds + PG8_SA(b, h) + aoff + m * 2048 + k * 1024); } while (0)
; #define PG8_LDB(dst, b, h) do { _Pragma("unroll") for (int n = 0; n < 2; ++n) _Pragma("unroll") for (int k = 0; k < 2; ++k) dst[n][k] = *(const PG8_LAS bf16x8*)(lds + PG8_SB(b, h) + boff + n * 2048 + k * 1024); } while (0)
; #define PG8_MMA(ai, bj, At, Bt) do { __builtin_amdgcn_s_setprio(1); _Pragma("unroll") for (int m = 0; m < 4; ++m) _Pragma("unroll") for (int n = 0; n < 2; ++n) _Pragma("unroll") for (int k = 0; k < 2; ++k) \
;         acc[ai][bj][m][n] = __builtin_amdgcn_mfma_f32_16x16x32_bf16(Bt[n][k], At[m][k], acc[ai][bj][m][n], 0, 0, 0); __builtin_amdgcn_s_setprio(0); } while (0)
; #define PG8_WAIT_V(n) asm volatile("s_waitcnt vmcnt(" #n ")" ::: "memory")
; #define PG8_WAIT_L(n) asm volatile("s_waitcnt lgkmcnt(" #n ")" ::: "memory")
; #define PG8_BAR __builtin_amdgcn_s_barrier()
; #define PG8_SCHED __builtin_amdgcn_sched_barrier(0)
; template <class Epi, class Sched, bool ALIGN_EPI = false, bool SP2 = false>
; __device__ __forceinline__ void gemm_phase(PG8_LAS unsigned char* lds, const Gemm g, const Sched& S, const Epi& E, int tid_in) {
;     ...
;             PG8_WAIT_V(8); PG8_WAIT_L(0); PG8_BAR; PG8_MMA(1, 0, At, B0); PG8_MMA(1, 1, At, B1); PG8_BAR; PG8_SCHED;
;             PG8_LDB(B0, 1, 0); PG8_LDB(B1, 1, 1); PG8_SCHED; PG8_LDA(At, 1, 0); PG8_STAGE(PG8_SA(0, 1), a2 + hstep, voffA);
;             PG8_WAIT_V(8); PG8_WAIT_L(0); PG8_BAR; PG8_MMA(0, 0, At, B0); PG8_MMA(0, 1, At, B1); PG8_BAR; PG8_SCHED;
	s_setprio 1
	s_waitcnt lgkmcnt(0)
	v_mfma_f32_16x16x32_bf16 v[76:79], v[40:43], v[182:185], v[76:79]
	v_mfma_f32_16x16x32_bf16 v[72:75], v[52:55], v[182:185], v[72:75]
	v_mfma_f32_16x16x32_bf16 v[56:59], v[40:43], v[198:201], v[56:59]
	v_mfma_f32_16x16x32_bf16 v[48:51], v[52:55], v[198:201], v[48:51]
	v_mfma_f32_16x16x32_bf16 v[28:31], v[40:43], v[206:209], v[28:31]
	v_mfma_f32_16x16x32_bf16 v[24:27], v[52:55], v[206:209], v[24:27]
	v_mfma_f32_16x16x32_bf16 v[12:15], v[40:43], v[226:229], v[12:15]
	v_mfma_f32_16x16x32_bf16 v[8:11], v[52:55], v[226:229], v[8:11]
	v_mfma_f32_16x16x32_bf16 v[76:79], v[44:47], v[194:197], v[76:79]
	v_mfma_f32_16x16x32_bf16 v[72:75], v[60:63], v[194:197], v[72:75]
	v_mfma_f32_16x16x32_bf16 v[56:59], v[44:47], v[202:205], v[56:59]
	v_mfma_f32_16x16x32_bf16 v[48:51], v[60:63], v[202:205], v[48:51]
	v_mfma_f32_16x16x32_bf16 v[28:31], v[44:47], v[210:213], v[28:31]
	v_mfma_f32_16x16x32_bf16 v[24:27], v[60:63], v[210:213], v[24:27]
	v_mfma_f32_16x16x32_bf16 v[12:15], v[44:47], v[232:235], v[12:15]
	v_mfma_f32_16x16x32_bf16 v[8:11], v[60:63], v[232:235], v[8:11]
	s_setprio 0
	s_setprio 1
	v_mfma_f32_16x16x32_bf16 v[36:39], v[146:149], v[198:201], v[36:39]
	v_mfma_f32_16x16x32_bf16 v[32:35], v[154:157], v[198:201], v[32:35]
	v_mfma_f32_16x16x32_bf16 v[20:23], v[146:149], v[206:209], v[20:23]
	v_mfma_f32_16x16x32_bf16 v[16:19], v[154:157], v[206:209], v[16:19]
	v_mfma_f32_16x16x32_bf16 v[4:7], v[146:149], v[226:229], v[4:7]
	v_mfma_f32_16x16x32_bf16 v[0:3], v[154:157], v[226:229], v[0:3]
	v_mfma_f32_16x16x32_bf16 v[40:43], v[146:149], v[182:185], v[68:71]
	v_mfma_f32_16x16x32_bf16 v[44:47], v[154:157], v[182:185], v[64:67]
	v_mfma_f32_16x16x32_bf16 v[36:39], v[150:153], v[202:205], v[36:39]
	v_mfma_f32_16x16x32_bf16 v[32:35], v[158:161], v[202:205], v[32:35]
	v_mfma_f32_16x16x32_bf16 v[20:23], v[150:153], v[210:213], v[20:23]
	v_mfma_f32_16x16x32_bf16 v[16:19], v[158:161], v[210:213], v[16:19]
	v_mfma_f32_16x16x32_bf16 v[4:7], v[150:153], v[232:235], v[4:7]
	v_mfma_f32_16x16x32_bf16 v[0:3], v[158:161], v[232:235], v[0:3]
	v_mfma_f32_16x16x32_bf16 v[40:43], v[150:153], v[194:197], v[40:43]
	s_barrier
	v_mfma_f32_16x16x32_bf16 v[44:47], v[158:161], v[194:197], v[44:47]
	s_setprio 0
	v_or_b32_e32 v52, 0x18000, v215
	v_add_u32_e32 v60, 0x18400, v215
	v_add_u32_e32 v64, 0x18800, v215
	v_add_u32_e32 v68, 0x18c00, v215
	v_or_b32_e32 v146, 0x1c000, v215
	v_add_u32_e32 v150, 0x1c400, v215
	v_add_u32_e32 v154, 0x1c800, v215
	v_add_u32_e32 v158, 0x1cc00, v215
	ds_read_b128 v[52:55], v52
	ds_read_b128 v[60:63], v60
	ds_read_b128 v[64:67], v64
	ds_read_b128 v[68:71], v68
	ds_read_b128 v[146:149], v146
	ds_read_b128 v[150:153], v150
	ds_read_b128 v[154:157], v154
	ds_read_b128 v[158:161], v158
	s_add_u32 s42, s42, s70
	s_addc_u32 s43, s43, 0
	s_mov_b32 m0, s58
	v_lshl_add_u64 v[180:181], s[42:43], 0, v[162:163]
	ds_read_b128 v[182:185], v214 offset:32768
	ds_read_b128 v[194:197], v214 offset:33792
	ds_read_b128 v[198:201], v214 offset:34816
	ds_read_b128 v[202:205], v214 offset:35840
	ds_read_b128 v[206:209], v214 offset:36864
	ds_read_b128 v[210:213], v214 offset:37888
	ds_read_b128 v[226:229], v214 offset:38912
	ds_read_b128 v[232:235], v214 offset:39936
	global_load_lds_dwordx4 v[180:181], off
	v_lshl_add_u64 v[180:181], s[42:43], 0, v[166:167]
	s_mov_b32 m0, s59
	s_nop 0
	global_load_lds_dwordx4 v[180:181], off
	s_waitcnt vmcnt(8)
	s_waitcnt lgkmcnt(0)
	s_barrier
	s_setprio 1
	s_waitcnt lgkmcnt(0)
	v_mfma_f32_16x16x32_bf16 v[142:145], v[52:55], v[182:185], v[142:145]
	v_mfma_f32_16x16x32_bf16 v[138:141], v[64:67], v[182:185], v[138:141]
	v_mfma_f32_16x16x32_bf16 v[126:129], v[52:55], v[198:201], v[126:129]
	v_mfma_f32_16x16x32_bf16 v[122:125], v[64:67], v[198:201], v[122:125]
	v_mfma_f32_16x16x32_bf16 v[110:113], v[52:55], v[206:209], v[110:113]
	v_mfma_f32_16x16x32_bf16 v[106:109], v[64:67], v[206:209], v[106:109]
	v_mfma_f32_16x16x32_bf16 v[94:97], v[52:55], v[226:229], v[94:97]
	v_mfma_f32_16x16x32_bf16 v[90:93], v[64:67], v[226:229], v[90:93]
	v_mfma_f32_16x16x32_bf16 v[142:145], v[60:63], v[194:197], v[142:145]
	v_mfma_f32_16x16x32_bf16 v[138:141], v[68:71], v[194:197], v[138:141]
	v_mfma_f32_16x16x32_bf16 v[126:129], v[60:63], v[202:205], v[126:129]
	v_mfma_f32_16x16x32_bf16 v[122:125], v[68:71], v[202:205], v[122:125]
	v_mfma_f32_16x16x32_bf16 v[110:113], v[60:63], v[210:213], v[110:113]
	v_mfma_f32_16x16x32_bf16 v[106:109], v[68:71], v[210:213], v[106:109]
	v_mfma_f32_16x16x32_bf16 v[94:97], v[60:63], v[232:235], v[94:97]
	v_mfma_f32_16x16x32_bf16 v[90:93], v[68:71], v[232:235], v[90:93]
	s_setprio 0
	s_setprio 1
	v_mfma_f32_16x16x32_bf16 v[134:137], v[146:149], v[182:185], v[134:137]
	v_mfma_f32_16x16x32_bf16 v[130:133], v[154:157], v[182:185], v[130:133]
	v_mfma_f32_16x16x32_bf16 v[118:121], v[146:149], v[198:201], v[118:121]
	v_mfma_f32_16x16x32_bf16 v[114:117], v[154:157], v[198:201], v[114:117]
	v_mfma_f32_16x16x32_bf16 v[102:105], v[146:149], v[206:209], v[102:105]
	v_mfma_f32_16x16x32_bf16 v[98:101], v[154:157], v[206:209], v[98:101]
	v_mfma_f32_16x16x32_bf16 v[86:89], v[146:149], v[226:229], v[86:89]
	v_mfma_f32_16x16x32_bf16 v[82:85], v[154:157], v[226:229], v[82:85]
	v_mfma_f32_16x16x32_bf16 v[134:137], v[150:153], v[194:197], v[134:137]
	v_mfma_f32_16x16x32_bf16 v[130:133], v[158:161], v[194:197], v[130:133]
	v_mfma_f32_16x16x32_bf16 v[118:121], v[150:153], v[202:205], v[118:121]
	v_mfma_f32_16x16x32_bf16 v[114:117], v[158:161], v[202:205], v[114:117]
	v_mfma_f32_16x16x32_bf16 v[102:105], v[150:153], v[210:213], v[102:105]
	v_mfma_f32_16x16x32_bf16 v[98:101], v[158:161], v[210:213], v[98:101]
	v_mfma_f32_16x16x32_bf16 v[86:89], v[150:153], v[232:235], v[86:89]
	s_barrier
; #define PG8_STAGE(bufoff, gbase, voff) do { _Pragma("unroll") for (int _i = 0; _i < 2; ++_i) \
;         __builtin_amdgcn_global_load_lds((const unsigned*)((const char*)(gbase) + (voff)[_i]), (PG8_LAS unsigned*)(lds + (bufoff) + ldsw + _i * 8192), 16, 0, 0); } while (0)
; #define PG8_LDA(dst, b, h) do { _Pragma("unroll") for (int m = 0; m < 4; ++m) _Pragma("unroll") for (int k = 0; k < 2; ++k) dst[m][k] = *(const PG8_LAS bf16x8*)(lds + PG8_SA(b, h) + aoff + m * 2048 + k * 1024); } while (0)
; #define PG8_MMA(ai, bj, At, Bt) do { __builtin_amdgcn_s_setprio(1); _Pragma("unroll") for (int m = 0; m < 4; ++m) _Pragma("unroll") for (int n = 0; n < 2; ++n) _Pragma("unroll") for (int k = 0; k < 2; ++k) \
;         acc[ai][bj][m][n] = __builtin_amdgcn_mfma_f32_16x16x32_bf16(Bt[n][k], At[m][k], acc[ai][bj][m][n], 0, 0, 0); __builtin_amdgcn_s_setprio(0); } while (0)
; #define PG8_WAIT_V(n) asm volatile("s_waitcnt vmcnt(" #n ")" ::: "memory")
; #define PG8_WAIT_L(n) asm volatile("s_waitcnt lgkmcnt(" #n ")" ::: "memory")
; #define PG8_BAR __builtin_amdgcn_s_barrier()
; #define PG8_SCHED __builtin_amdgcn_sched_barrier(0)
; template <class Epi, class Sched, bool ALIGN_EPI = false, bool SP2 = false>
; __device__ __forceinline__ void gemm_phase(PG8_LAS unsigned char* lds, const Gemm g, const Sched& S, const Epi& E, int tid_in) {
;     ...
;             PG8_WAIT_V(8); PG8_WAIT_L(0); PG8_BAR; PG8_MMA(0, 0, At, B0); PG8_MMA(0, 1, At, B1); PG8_BAR; PG8_SCHED;
;             PG8_LDA(At, 1, 1); PG8_STAGE(PG8_SB(1, 0), b3, voffB); PG8_STAGE(PG8_SB(1, 1), b3 + hstep, voffB); PG8_STAGE(PG8_SA(1, 0), a3, voffA);
;             PG8_WAIT_V(8); PG8_WAIT_L(0); PG8_BAR; PG8_MMA(1, 0, At, B0); PG8_MMA(1, 1, At, B1); PG8_BAR; PG8_SCHED;
;     ...
;         if constexpr (ALIGN_EPI) { if (wr == 0) PG8_BAR; }
	v_mfma_f32_16x16x32_bf16 v[82:85], v[158:161], v[232:235], v[82:85]
	s_setprio 0
	s_mov_b32 m0, s64
	v_lshl_add_u64 v[180:181], v[218:219], 0, s[48:49]
	ds_read_b128 v[182:185], v214 offset:49152
	ds_read_b128 v[194:197], v214 offset:50176
	ds_read_b128 v[198:201], v214 offset:51200
	ds_read_b128 v[202:205], v214 offset:52224
	ds_read_b128 v[206:209], v214 offset:53248
	ds_read_b128 v[210:213], v214 offset:54272
	ds_read_b128 v[226:229], v214 offset:55296
	ds_read_b128 v[232:235], v214 offset:56320
	global_load_lds_dwordx4 v[180:181], off
	v_lshl_add_u64 v[180:181], v[250:251], 0, s[48:49]
	s_mov_b32 m0, s65
	v_lshl_add_u64 v[178:179], v[178:179], 0, s[48:49]
	global_load_lds_dwordx4 v[180:181], off
	v_lshl_add_u64 v[180:181], v[236:237], 0, s[48:49]
	s_mov_b32 m0, s61
	s_nop 0
	global_load_lds_dwordx4 v[180:181], off
	v_lshl_add_u64 v[180:181], v[238:239], 0, s[48:49]
	s_mov_b32 m0, s62
	s_nop 0
	global_load_lds_dwordx4 v[180:181], off
	v_lshl_add_u64 v[180:181], v[240:241], 0, s[48:49]
	s_mov_b32 m0, s72
	s_nop 0
	global_load_lds_dwordx4 v[180:181], off
	s_mov_b32 m0, s73
	s_nop 0
	global_load_lds_dwordx4 v[178:179], off
	s_waitcnt vmcnt(8)
	s_waitcnt lgkmcnt(0)
	s_barrier
	s_setprio 1
	s_waitcnt lgkmcnt(0)
	v_mfma_f32_16x16x32_bf16 v[76:79], v[52:55], v[182:185], v[76:79]
	v_mfma_f32_16x16x32_bf16 v[72:75], v[64:67], v[182:185], v[72:75]
	v_mfma_f32_16x16x32_bf16 v[56:59], v[52:55], v[198:201], v[56:59]
	v_mfma_f32_16x16x32_bf16 v[48:51], v[64:67], v[198:201], v[48:51]
	v_mfma_f32_16x16x32_bf16 v[28:31], v[52:55], v[206:209], v[28:31]
	v_mfma_f32_16x16x32_bf16 v[24:27], v[64:67], v[206:209], v[24:27]
	v_mfma_f32_16x16x32_bf16 v[12:15], v[52:55], v[226:229], v[12:15]
	v_mfma_f32_16x16x32_bf16 v[8:11], v[64:67], v[226:229], v[8:11]
	v_mfma_f32_16x16x32_bf16 v[76:79], v[60:63], v[194:197], v[76:79]
	v_mfma_f32_16x16x32_bf16 v[72:75], v[68:71], v[194:197], v[72:75]
	v_mfma_f32_16x16x32_bf16 v[56:59], v[60:63], v[202:205], v[56:59]
	v_mfma_f32_16x16x32_bf16 v[48:51], v[68:71], v[202:205], v[48:51]
	v_mfma_f32_16x16x32_bf16 v[28:31], v[60:63], v[210:213], v[28:31]
	v_mfma_f32_16x16x32_bf16 v[24:27], v[68:71], v[210:213], v[24:27]
	v_mfma_f32_16x16x32_bf16 v[12:15], v[60:63], v[232:235], v[12:15]
	v_mfma_f32_16x16x32_bf16 v[8:11], v[68:71], v[232:235], v[8:11]
	s_setprio 0
	s_setprio 1
	v_mfma_f32_16x16x32_bf16 v[40:43], v[146:149], v[182:185], v[40:43]
	v_mfma_f32_16x16x32_bf16 v[68:71], v[150:153], v[194:197], v[40:43]
	v_mfma_f32_16x16x32_bf16 v[40:43], v[154:157], v[182:185], v[44:47]
	v_mfma_f32_16x16x32_bf16 v[36:39], v[146:149], v[198:201], v[36:39]
	v_mfma_f32_16x16x32_bf16 v[32:35], v[154:157], v[198:201], v[32:35]
	v_mfma_f32_16x16x32_bf16 v[20:23], v[146:149], v[206:209], v[20:23]
	v_mfma_f32_16x16x32_bf16 v[16:19], v[154:157], v[206:209], v[16:19]
	v_mfma_f32_16x16x32_bf16 v[4:7], v[146:149], v[226:229], v[4:7]
	v_mfma_f32_16x16x32_bf16 v[0:3], v[154:157], v[226:229], v[0:3]
	v_mfma_f32_16x16x32_bf16 v[64:67], v[158:161], v[194:197], v[40:43]
	v_mfma_f32_16x16x32_bf16 v[36:39], v[150:153], v[202:205], v[36:39]
	v_mfma_f32_16x16x32_bf16 v[32:35], v[158:161], v[202:205], v[32:35]
	v_mfma_f32_16x16x32_bf16 v[20:23], v[150:153], v[210:213], v[20:23]
	v_mfma_f32_16x16x32_bf16 v[16:19], v[158:161], v[210:213], v[16:19]
	v_mfma_f32_16x16x32_bf16 v[4:7], v[150:153], v[232:235], v[4:7]
	s_barrier
	v_mfma_f32_16x16x32_bf16 v[0:3], v[158:161], v[232:235], v[0:3]
	s_setprio 0
	s_add_u32 s40, s40, 0x100
	s_addc_u32 s41, s41, 0
	s_add_u32 s26, s26, 0x100
	s_addc_u32 s27, s27, 0
	s_cmp_ge_u32 s44, s66
	s_mov_b32 s42, s44
	s_cbranch_scc0 .LBB0_508
	s_and_b64 vcc, exec, s[78:79]
	s_cbranch_vccz .LBB0_511
	s_barrier

; #define PG8_STAGE(bufoff, gbase, voff) do { _Pragma("unroll") for (int _i = 0; _i < 2; ++_i) \
;         __builtin_amdgcn_global_load_lds((const unsigned*)((const char*)(gbase) + (voff)[_i]), (PG8_LAS unsigned*)(lds + (bufoff) + ldsw + _i * 8192), 16, 0, 0); } while (0)
; #define PG8_LDA(dst, b, h) do { _Pragma("unroll") for (int m = 0; m < 4; ++m) _Pragma("unroll") for (int k = 0; k < 2; ++k) dst[m][k] = *(const PG8_LAS bf16x8*)(lds + PG8_SA(b, h) + aoff + m * 2048 + k * 1024); } while (0)
; #define PG8_LDB(dst, b, h) do { _Pragma("unroll") for (int n = 0; n < 2; ++n) _Pragma("unroll") for (int k = 0; k < 2; ++k) dst[n][k] = *(const PG8_LAS bf16x8*)(lds + PG8_SB(b, h) + boff + n * 2048 + k * 1024); } while (0)
; #define PG8_MMA(ai, bj, At, Bt) do { __builtin_amdgcn_s_setprio(1); _Pragma("unroll") for (int m = 0; m < 4; ++m) _Pragma("unroll") for (int n = 0; n < 2; ++n) _Pragma("unroll") for (int k = 0; k < 2; ++k) \
;         acc[ai][bj][m][n] = __builtin_amdgcn_mfma_f32_16x16x32_bf16(Bt[n][k], At[m][k], acc[ai][bj][m][n], 0, 0, 0); __builtin_amdgcn_s_setprio(0); } while (0)
; #define PG8_WAIT_V(n) asm volatile("s_waitcnt vmcnt(" #n ")" ::: "memory")
; #define PG8_WAIT_L(n) asm volatile("s_waitcnt lgkmcnt(" #n ")" ::: "memory")
; #define PG8_BAR __builtin_amdgcn_s_barrier()
; #define PG8_SCHED __builtin_amdgcn_sched_barrier(0)
; template <class Epi, class Sched, bool ALIGN_EPI = false, bool SP2 = false>
; __device__ __forceinline__ void gemm_phase(PG8_LAS unsigned char* lds, const Gemm g, const Sched& S, const Epi& E, int tid_in) {
;     ...
;             PG8_LDB(B0, 0, 0); PG8_LDB(B1, 0, 1); PG8_SCHED; PG8_LDA(At, 0, 0); PG8_STAGE(PG8_SA(1, 1), a1 + hstep, voffA);
;             PG8_WAIT_V(8); PG8_WAIT_L(0); PG8_BAR; PG8_MMA(0, 0, At, B0); PG8_MMA(0, 1, At, B1); PG8_BAR; PG8_SCHED;
;             PG8_LDA(At, 0, 1); PG8_STAGE(PG8_SB(0, 0), b2, voffB); PG8_STAGE(PG8_SB(0, 1), b2 + hstep, voffB); PG8_STAGE(PG8_SA(0, 0), a2, voffA);
;             PG8_WAIT_V(8); PG8_WAIT_L(0); PG8_BAR; PG8_MMA(1, 0, At, B0); PG8_MMA(1, 1, At, B1); PG8_BAR; PG8_SCHED;
.LBB0_780:
	v_or_b32_e32 v142, 0x10000, v145
	v_add_u32_e32 v143, 0x10400, v145
	ds_read_b128 v[148:151], v142
	ds_read_b128 v[152:155], v143
	v_add_u32_e32 v142, 0x10800, v145
	v_add_u32_e32 v143, 0x10c00, v145
	ds_read_b128 v[156:159], v142
	ds_read_b128 v[160:163], v143
	v_or_b32_e32 v142, 0x14000, v145
	v_add_u32_e32 v143, 0x14400, v145
	ds_read_b128 v[164:167], v142
	ds_read_b128 v[168:171], v143
	v_add_u32_e32 v142, 0x14800, v145
	v_add_u32_e32 v143, 0x14c00, v145
	ds_read_b128 v[172:175], v142
	ds_read_b128 v[194:197], v143
	s_add_u32 s70, s68, 0xfffc0080
	s_addc_u32 s71, s69, -1
	s_cmp_eq_u32 s82, 12
	s_cselect_b32 s73, s45, s71
	s_cselect_b32 s72, s78, s70
	s_cselect_b32 s71, s43, s81
	s_cselect_b32 s70, s79, s80
	v_lshl_add_u64 v[142:143], s[68:69], 0, v[138:139]
	s_add_i32 m0, s22, 0xc000
	ds_read_b128 v[198:201], v144
	ds_read_b128 v[202:205], v144 offset:1024
	ds_read_b128 v[206:209], v144 offset:2048
	ds_read_b128 v[210:213], v144 offset:3072
	ds_read_b128 v[214:217], v144 offset:4096
	ds_read_b128 v[248:251], v144 offset:5120
	ds_read_b128 v[232:235], v144 offset:6144
	ds_read_b128 v[226:229], v144 offset:7168
	global_load_lds_dwordx4 v[142:143], off
	v_lshl_add_u64 v[142:143], s[68:69], 0, v[140:141]
	s_add_i32 m0, s22, 0xe000
	s_nop 0
	global_load_lds_dwordx4 v[142:143], off
	s_waitcnt vmcnt(8)
	s_waitcnt lgkmcnt(0)
	s_barrier
	s_setprio 1
	s_waitcnt lgkmcnt(0)
	v_mfma_f32_16x16x32_bf16 v[126:129], v[148:151], v[198:201], v[126:129]
	v_mfma_f32_16x16x32_bf16 v[118:121], v[156:159], v[198:201], v[118:121]
	v_mfma_f32_16x16x32_bf16 v[110:113], v[148:151], v[206:209], v[110:113]
	v_mfma_f32_16x16x32_bf16 v[102:105], v[156:159], v[206:209], v[102:105]
	v_mfma_f32_16x16x32_bf16 v[94:97], v[148:151], v[214:217], v[94:97]
	v_mfma_f32_16x16x32_bf16 v[86:89], v[156:159], v[214:217], v[86:89]
	v_mfma_f32_16x16x32_bf16 v[76:79], v[148:151], v[232:235], v[76:79]
	v_mfma_f32_16x16x32_bf16 v[68:71], v[156:159], v[232:235], v[68:71]
	v_mfma_f32_16x16x32_bf16 v[126:129], v[152:155], v[202:205], v[126:129]
	v_mfma_f32_16x16x32_bf16 v[118:121], v[160:163], v[202:205], v[118:121]
	v_mfma_f32_16x16x32_bf16 v[110:113], v[152:155], v[210:213], v[110:113]
	v_mfma_f32_16x16x32_bf16 v[102:105], v[160:163], v[210:213], v[102:105]
	v_mfma_f32_16x16x32_bf16 v[94:97], v[152:155], v[248:251], v[94:97]
	v_mfma_f32_16x16x32_bf16 v[86:89], v[160:163], v[248:251], v[86:89]
	v_mfma_f32_16x16x32_bf16 v[76:79], v[152:155], v[226:229], v[76:79]
	v_mfma_f32_16x16x32_bf16 v[68:71], v[160:163], v[226:229], v[68:71]
	s_setprio 0
	s_setprio 1
	v_mfma_f32_16x16x32_bf16 v[122:125], v[164:167], v[198:201], v[122:125]
	v_mfma_f32_16x16x32_bf16 v[114:117], v[172:175], v[198:201], v[114:117]
	v_mfma_f32_16x16x32_bf16 v[106:109], v[164:167], v[206:209], v[106:109]
	v_mfma_f32_16x16x32_bf16 v[98:101], v[172:175], v[206:209], v[98:101]
	v_mfma_f32_16x16x32_bf16 v[90:93], v[164:167], v[214:217], v[90:93]
	v_mfma_f32_16x16x32_bf16 v[82:85], v[172:175], v[214:217], v[82:85]
	v_mfma_f32_16x16x32_bf16 v[72:75], v[164:167], v[232:235], v[72:75]
	v_mfma_f32_16x16x32_bf16 v[64:67], v[172:175], v[232:235], v[64:67]
	v_mfma_f32_16x16x32_bf16 v[122:125], v[168:171], v[202:205], v[122:125]
	v_mfma_f32_16x16x32_bf16 v[114:117], v[194:197], v[202:205], v[114:117]
	v_mfma_f32_16x16x32_bf16 v[106:109], v[168:171], v[210:213], v[106:109]
	v_mfma_f32_16x16x32_bf16 v[98:101], v[194:197], v[210:213], v[98:101]
	v_mfma_f32_16x16x32_bf16 v[90:93], v[168:171], v[248:251], v[90:93]
	v_mfma_f32_16x16x32_bf16 v[82:85], v[194:197], v[248:251], v[82:85]
	v_mfma_f32_16x16x32_bf16 v[72:75], v[168:171], v[226:229], v[72:75]
	s_barrier
	v_mfma_f32_16x16x32_bf16 v[64:67], v[194:197], v[226:229], v[64:67]
	s_setprio 0
	s_mov_b32 m0, s24
	v_lshl_add_u64 v[142:143], s[70:71], 0, v[134:135]
	s_add_u32 s84, s70, 0x40000
	ds_read_b128 v[198:201], v144 offset:16384
	ds_read_b128 v[202:205], v144 offset:17408
	ds_read_b128 v[206:209], v144 offset:18432
	ds_read_b128 v[210:213], v144 offset:19456
	ds_read_b128 v[214:217], v144 offset:20480
	ds_read_b128 v[226:229], v144 offset:21504
	ds_read_b128 v[232:235], v144 offset:22528
	ds_read_b128 v[248:251], v144 offset:23552
	global_load_lds_dwordx4 v[142:143], off
	v_lshl_add_u64 v[176:177], s[70:71], 0, v[130:131]
	s_mov_b32 m0, s25
	s_addc_u32 s85, s71, 0
	global_load_lds_dwordx4 v[176:177], off
	v_lshl_add_u64 v[182:183], s[84:85], 0, v[134:135]
	s_mov_b32 m0, s26
	v_lshl_add_u64 v[184:185], s[72:73], 0, v[132:133]
	global_load_lds_dwordx4 v[182:183], off
	v_lshl_add_u64 v[182:183], s[84:85], 0, v[130:131]
	s_mov_b32 m0, s27
	s_nop 0
	global_load_lds_dwordx4 v[182:183], off
	v_lshl_add_u64 v[182:183], s[72:73], 0, v[136:137]
	s_mov_b32 m0, s22
	s_nop 0
	global_load_lds_dwordx4 v[182:183], off
	s_mov_b32 m0, s29
	s_nop 0
	global_load_lds_dwordx4 v[184:185], off
	s_waitcnt vmcnt(8)
	s_waitcnt lgkmcnt(0)
	s_barrier
; #define PG8_STAGE(bufoff, gbase, voff) do { _Pragma("unroll") for (int _i = 0; _i < 2; ++_i) \
;         __builtin_amdgcn_global_load_lds((const unsigned*)((const char*)(gbase) + (voff)[_i]), (PG8_LAS unsigned*)(lds + (bufoff) + ldsw + _i * 8192), 16, 0, 0); } while (0)
; #define PG8_LDA(dst, b, h) do { _Pragma("unroll") for (int m = 0; m < 4; ++m) _Pragma("unroll") for (int k = 0; k < 2; ++k) dst[m][k] = *(const PG8_LAS bf16x8*)(lds + PG8_SA(b, h) + aoff + m * 2048 + k * 1024); } while (0)
; #define PG8_LDB(dst, b, h) do { _Pragma("unroll") for (int n = 0; n < 2; ++n) _Pragma("unroll") for (int k = 0; k < 2; ++k) dst[n][k] = *(const PG8_LAS bf16x8*)(lds + PG8_SB(b, h) + boff + n * 2048 + k * 1024); } while (0)
; #define PG8_MMA(ai, bj, At, Bt) do { __builtin_amdgcn_s_setprio(1); _Pragma("unroll") for (int m = 0; m < 4; ++m) _Pragma("unroll") for (int n = 0; n < 2; ++n) _Pragma("unroll") for (int k = 0; k < 2; ++k) \
;         acc[ai][bj][m][n] = __builtin_amdgcn_mfma_f32_16x16x32_bf16(Bt[n][k], At[m][k], acc[ai][bj][m][n], 0, 0, 0); __builtin_amdgcn_s_setprio(0); } while (0)
; #define PG8_WAIT_V(n) asm volatile("s_waitcnt vmcnt(" #n ")" ::: "memory")
; #define PG8_WAIT_L(n) asm volatile("s_waitcnt lgkmcnt(" #n ")" ::: "memory")
; #define PG8_BAR __builtin_amdgcn_s_barrier()
; #define PG8_SCHED __builtin_amdgcn_sched_barrier(0)
; template <class Epi, class Sched, bool ALIGN_EPI = false, bool SP2 = false>
; __device__ __forceinline__ void gemm_phase(PG8_LAS unsigned char* lds, const Gemm g, const Sched& S, const Epi& E, int tid_in) {
;     ...
;             PG8_WAIT_V(8); PG8_WAIT_L(0); PG8_BAR; PG8_MMA(1, 0, At, B0); PG8_MMA(1, 1, At, B1); PG8_BAR; PG8_SCHED;
;             PG8_LDB(B0, 1, 0); PG8_LDB(B1, 1, 1); PG8_SCHED; PG8_LDA(At, 1, 0); PG8_STAGE(PG8_SA(0, 1), a2 + hstep, voffA);
;             PG8_WAIT_V(8); PG8_WAIT_L(0); PG8_BAR; PG8_MMA(0, 0, At, B0); PG8_MMA(0, 1, At, B1); PG8_BAR; PG8_SCHED;
	s_setprio 1
	s_waitcnt lgkmcnt(0)
	v_mfma_f32_16x16x32_bf16 v[60:63], v[148:151], v[198:201], v[60:63]
	v_mfma_f32_16x16x32_bf16 v[52:55], v[156:159], v[198:201], v[52:55]
	v_mfma_f32_16x16x32_bf16 v[44:47], v[148:151], v[206:209], v[44:47]
	v_mfma_f32_16x16x32_bf16 v[36:39], v[156:159], v[206:209], v[36:39]
	v_mfma_f32_16x16x32_bf16 v[28:31], v[148:151], v[214:217], v[28:31]
	v_mfma_f32_16x16x32_bf16 v[20:23], v[156:159], v[214:217], v[20:23]
	v_mfma_f32_16x16x32_bf16 v[12:15], v[148:151], v[232:235], v[12:15]
	v_mfma_f32_16x16x32_bf16 v[4:7], v[156:159], v[232:235], v[4:7]
	v_mfma_f32_16x16x32_bf16 v[60:63], v[152:155], v[202:205], v[60:63]
	v_mfma_f32_16x16x32_bf16 v[52:55], v[160:163], v[202:205], v[52:55]
	v_mfma_f32_16x16x32_bf16 v[44:47], v[152:155], v[210:213], v[44:47]
	v_mfma_f32_16x16x32_bf16 v[36:39], v[160:163], v[210:213], v[36:39]
	v_mfma_f32_16x16x32_bf16 v[28:31], v[152:155], v[226:229], v[28:31]
	v_mfma_f32_16x16x32_bf16 v[20:23], v[160:163], v[226:229], v[20:23]
	v_mfma_f32_16x16x32_bf16 v[12:15], v[152:155], v[248:251], v[12:15]
	v_mfma_f32_16x16x32_bf16 v[4:7], v[160:163], v[248:251], v[4:7]
	s_setprio 0
	s_setprio 1
	v_mfma_f32_16x16x32_bf16 v[56:59], v[164:167], v[198:201], v[56:59]
	v_mfma_f32_16x16x32_bf16 v[48:51], v[172:175], v[198:201], v[48:51]
	v_mfma_f32_16x16x32_bf16 v[40:43], v[164:167], v[206:209], v[40:43]
	v_mfma_f32_16x16x32_bf16 v[32:35], v[172:175], v[206:209], v[32:35]
	v_mfma_f32_16x16x32_bf16 v[24:27], v[164:167], v[214:217], v[24:27]
	v_mfma_f32_16x16x32_bf16 v[16:19], v[172:175], v[214:217], v[16:19]
	v_mfma_f32_16x16x32_bf16 v[8:11], v[164:167], v[232:235], v[8:11]
	v_mfma_f32_16x16x32_bf16 v[0:3], v[172:175], v[232:235], v[0:3]
	v_mfma_f32_16x16x32_bf16 v[56:59], v[168:171], v[202:205], v[56:59]
	v_mfma_f32_16x16x32_bf16 v[48:51], v[194:197], v[202:205], v[48:51]
	v_mfma_f32_16x16x32_bf16 v[40:43], v[168:171], v[210:213], v[40:43]
	v_mfma_f32_16x16x32_bf16 v[32:35], v[194:197], v[210:213], v[32:35]
	v_mfma_f32_16x16x32_bf16 v[24:27], v[168:171], v[226:229], v[24:27]
	v_mfma_f32_16x16x32_bf16 v[16:19], v[194:197], v[226:229], v[16:19]
	v_mfma_f32_16x16x32_bf16 v[8:11], v[168:171], v[248:251], v[8:11]
	s_barrier
	v_mfma_f32_16x16x32_bf16 v[0:3], v[194:197], v[248:251], v[0:3]
	s_setprio 0
	v_or_b32_e32 v148, 0x18000, v145
	v_add_u32_e32 v152, 0x18400, v145
	v_add_u32_e32 v156, 0x18800, v145
	v_add_u32_e32 v160, 0x18c00, v145
	v_or_b32_e32 v164, 0x1c000, v145
	v_add_u32_e32 v168, 0x1c400, v145
	v_add_u32_e32 v172, 0x1c800, v145
	ds_read_b128 v[148:151], v148
	ds_read_b128 v[152:155], v152
	ds_read_b128 v[156:159], v156
	ds_read_b128 v[160:163], v160
	ds_read_b128 v[164:167], v164
	ds_read_b128 v[168:171], v168
	v_add_u32_e32 v178, 0x1cc00, v145
	ds_read_b128 v[172:175], v172
	ds_read_b128 v[194:197], v178
	s_add_u32 s72, s72, 0x40000
	s_addc_u32 s73, s73, 0
	s_mov_b32 m0, s31
	v_lshl_add_u64 v[218:219], s[72:73], 0, v[136:137]
	ds_read_b128 v[198:201], v144 offset:32768
	ds_read_b128 v[202:205], v144 offset:33792
	ds_read_b128 v[206:209], v144 offset:34816
	ds_read_b128 v[210:213], v144 offset:35840
	ds_read_b128 v[214:217], v144 offset:36864
	ds_read_b128 v[226:229], v144 offset:37888
	ds_read_b128 v[232:235], v144 offset:38912
	ds_read_b128 v[248:251], v144 offset:39936
	global_load_lds_dwordx4 v[218:219], off
	v_lshl_add_u64 v[218:219], s[72:73], 0, v[132:133]
	s_mov_b32 m0, s57
	s_nop 0
	global_load_lds_dwordx4 v[218:219], off
	s_waitcnt vmcnt(8)
	s_waitcnt lgkmcnt(0)
	s_barrier
	s_setprio 1
	s_waitcnt lgkmcnt(0)
	v_mfma_f32_16x16x32_bf16 v[126:129], v[148:151], v[198:201], v[126:129]
	v_mfma_f32_16x16x32_bf16 v[118:121], v[156:159], v[198:201], v[118:121]
	v_mfma_f32_16x16x32_bf16 v[110:113], v[148:151], v[206:209], v[110:113]
	v_mfma_f32_16x16x32_bf16 v[102:105], v[156:159], v[206:209], v[102:105]
	v_mfma_f32_16x16x32_bf16 v[94:97], v[148:151], v[214:217], v[94:97]
	v_mfma_f32_16x16x32_bf16 v[86:89], v[156:159], v[214:217], v[86:89]
	v_mfma_f32_16x16x32_bf16 v[76:79], v[148:151], v[232:235], v[76:79]
	v_mfma_f32_16x16x32_bf16 v[68:71], v[156:159], v[232:235], v[68:71]
	v_mfma_f32_16x16x32_bf16 v[126:129], v[152:155], v[202:205], v[126:129]
	v_mfma_f32_16x16x32_bf16 v[118:121], v[160:163], v[202:205], v[118:121]
	v_mfma_f32_16x16x32_bf16 v[110:113], v[152:155], v[210:213], v[110:113]
	v_mfma_f32_16x16x32_bf16 v[102:105], v[160:163], v[210:213], v[102:105]
	v_mfma_f32_16x16x32_bf16 v[94:97], v[152:155], v[226:229], v[94:97]
	v_mfma_f32_16x16x32_bf16 v[86:89], v[160:163], v[226:229], v[86:89]
	v_mfma_f32_16x16x32_bf16 v[76:79], v[152:155], v[248:251], v[76:79]
	v_mfma_f32_16x16x32_bf16 v[68:71], v[160:163], v[248:251], v[68:71]
	s_setprio 0
	s_setprio 1
	v_mfma_f32_16x16x32_bf16 v[122:125], v[164:167], v[198:201], v[122:125]
	v_mfma_f32_16x16x32_bf16 v[114:117], v[172:175], v[198:201], v[114:117]
	v_mfma_f32_16x16x32_bf16 v[106:109], v[164:167], v[206:209], v[106:109]
	v_mfma_f32_16x16x32_bf16 v[98:101], v[172:175], v[206:209], v[98:101]
	v_mfma_f32_16x16x32_bf16 v[90:93], v[164:167], v[214:217], v[90:93]
	v_mfma_f32_16x16x32_bf16 v[82:85], v[172:175], v[214:217], v[82:85]
	v_mfma_f32_16x16x32_bf16 v[72:75], v[164:167], v[232:235], v[72:75]
	v_mfma_f32_16x16x32_bf16 v[64:67], v[172:175], v[232:235], v[64:67]
	v_mfma_f32_16x16x32_bf16 v[122:125], v[168:171], v[202:205], v[122:125]
	v_mfma_f32_16x16x32_bf16 v[114:117], v[194:197], v[202:205], v[114:117]
	v_mfma_f32_16x16x32_bf16 v[106:109], v[168:171], v[210:213], v[106:109]
	v_mfma_f32_16x16x32_bf16 v[98:101], v[194:197], v[210:213], v[98:101]
	v_mfma_f32_16x16x32_bf16 v[90:93], v[168:171], v[226:229], v[90:93]
	v_mfma_f32_16x16x32_bf16 v[82:85], v[194:197], v[226:229], v[82:85]
	v_mfma_f32_16x16x32_bf16 v[72:75], v[168:171], v[248:251], v[72:75]
	s_barrier
; #define PG8_STAGE(bufoff, gbase, voff) do { _Pragma("unroll") for (int _i = 0; _i < 2; ++_i) \
;         __builtin_amdgcn_global_load_lds((const unsigned*)((const char*)(gbase) + (voff)[_i]), (PG8_LAS unsigned*)(lds + (bufoff) + ldsw + _i * 8192), 16, 0, 0); } while (0)
; #define PG8_LDA(dst, b, h) do { _Pragma("unroll") for (int m = 0; m < 4; ++m) _Pragma("unroll") for (int k = 0; k < 2; ++k) dst[m][k] = *(const PG8_LAS bf16x8*)(lds + PG8_SA(b, h) + aoff + m * 2048 + k * 1024); } while (0)
; #define PG8_MMA(ai, bj, At, Bt) do { __builtin_amdgcn_s_setprio(1); _Pragma("unroll") for (int m = 0; m < 4; ++m) _Pragma("unroll") for (int n = 0; n < 2; ++n) _Pragma("unroll") for (int k = 0; k < 2; ++k) \
;         acc[ai][bj][m][n] = __builtin_amdgcn_mfma_f32_16x16x32_bf16(Bt[n][k], At[m][k], acc[ai][bj][m][n], 0, 0, 0); __builtin_amdgcn_s_setprio(0); } while (0)
; #define PG8_WAIT_V(n) asm volatile("s_waitcnt vmcnt(" #n ")" ::: "memory")
; #define PG8_WAIT_L(n) asm volatile("s_waitcnt lgkmcnt(" #n ")" ::: "memory")
; #define PG8_BAR __builtin_amdgcn_s_barrier()
; #define PG8_SCHED __builtin_amdgcn_sched_barrier(0)
; template <class Epi, class Sched, bool ALIGN_EPI = false, bool SP2 = false>
; __device__ __forceinline__ void gemm_phase(PG8_LAS unsigned char* lds, const Gemm g, const Sched& S, const Epi& E, int tid_in) {
;     ...
;             PG8_WAIT_V(8); PG8_WAIT_L(0); PG8_BAR; PG8_MMA(0, 0, At, B0); PG8_MMA(0, 1, At, B1); PG8_BAR; PG8_SCHED;
;             PG8_LDA(At, 1, 1); PG8_STAGE(PG8_SB(1, 0), b3, voffB); PG8_STAGE(PG8_SB(1, 1), b3 + hstep, voffB); PG8_STAGE(PG8_SA(1, 0), a3, voffA);
;             PG8_WAIT_V(8); PG8_WAIT_L(0); PG8_BAR; PG8_MMA(1, 0, At, B0); PG8_MMA(1, 1, At, B1); PG8_BAR; PG8_SCHED;
;     ...
;         if constexpr (ALIGN_EPI) { if (wr == 0) PG8_BAR; }
	v_mfma_f32_16x16x32_bf16 v[64:67], v[194:197], v[248:251], v[64:67]
	s_setprio 0
	s_mov_b32 m0, s58
	v_lshl_add_u64 v[142:143], v[142:143], 0, s[48:49]
	s_add_u32 s70, s70, 0x40080
	ds_read_b128 v[198:201], v144 offset:49152
	ds_read_b128 v[202:205], v144 offset:50176
	ds_read_b128 v[206:209], v144 offset:51200
	ds_read_b128 v[210:213], v144 offset:52224
	ds_read_b128 v[214:217], v144 offset:53248
	ds_read_b128 v[226:229], v144 offset:54272
	ds_read_b128 v[232:235], v144 offset:55296
	ds_read_b128 v[248:251], v144 offset:56320
	global_load_lds_dwordx4 v[142:143], off
	v_lshl_add_u64 v[142:143], v[176:177], 0, s[48:49]
	s_mov_b32 m0, s59
	s_addc_u32 s71, s71, 0
	global_load_lds_dwordx4 v[142:143], off
	v_lshl_add_u64 v[142:143], s[70:71], 0, v[134:135]
	s_mov_b32 m0, s63
	s_nop 0
	global_load_lds_dwordx4 v[142:143], off
	v_lshl_add_u64 v[142:143], s[70:71], 0, v[130:131]
	s_mov_b32 m0, s67
	s_nop 0
	global_load_lds_dwordx4 v[142:143], off
	v_lshl_add_u64 v[142:143], v[182:183], 0, s[48:49]
	s_mov_b32 m0, s61
	s_nop 0
	global_load_lds_dwordx4 v[142:143], off
	v_lshl_add_u64 v[142:143], v[184:185], 0, s[48:49]
	s_mov_b32 m0, s62
	s_nop 0
	global_load_lds_dwordx4 v[142:143], off
	s_waitcnt vmcnt(8)
	s_waitcnt lgkmcnt(0)
	s_barrier
	s_setprio 1
	s_waitcnt lgkmcnt(0)
	v_mfma_f32_16x16x32_bf16 v[60:63], v[148:151], v[198:201], v[60:63]
	v_mfma_f32_16x16x32_bf16 v[52:55], v[156:159], v[198:201], v[52:55]
	v_mfma_f32_16x16x32_bf16 v[44:47], v[148:151], v[206:209], v[44:47]
	v_mfma_f32_16x16x32_bf16 v[36:39], v[156:159], v[206:209], v[36:39]
	v_mfma_f32_16x16x32_bf16 v[28:31], v[148:151], v[214:217], v[28:31]
	v_mfma_f32_16x16x32_bf16 v[20:23], v[156:159], v[214:217], v[20:23]
	v_mfma_f32_16x16x32_bf16 v[12:15], v[148:151], v[232:235], v[12:15]
	v_mfma_f32_16x16x32_bf16 v[4:7], v[156:159], v[232:235], v[4:7]
	v_mfma_f32_16x16x32_bf16 v[60:63], v[152:155], v[202:205], v[60:63]
	v_mfma_f32_16x16x32_bf16 v[52:55], v[160:163], v[202:205], v[52:55]
	v_mfma_f32_16x16x32_bf16 v[44:47], v[152:155], v[210:213], v[44:47]
	v_mfma_f32_16x16x32_bf16 v[36:39], v[160:163], v[210:213], v[36:39]
	v_mfma_f32_16x16x32_bf16 v[28:31], v[152:155], v[226:229], v[28:31]
	v_mfma_f32_16x16x32_bf16 v[20:23], v[160:163], v[226:229], v[20:23]
	v_mfma_f32_16x16x32_bf16 v[12:15], v[152:155], v[248:251], v[12:15]
	v_mfma_f32_16x16x32_bf16 v[4:7], v[160:163], v[248:251], v[4:7]
	s_setprio 0
	s_setprio 1
	v_mfma_f32_16x16x32_bf16 v[56:59], v[164:167], v[198:201], v[56:59]
	v_mfma_f32_16x16x32_bf16 v[48:51], v[172:175], v[198:201], v[48:51]
	v_mfma_f32_16x16x32_bf16 v[40:43], v[164:167], v[206:209], v[40:43]
	v_mfma_f32_16x16x32_bf16 v[32:35], v[172:175], v[206:209], v[32:35]
	v_mfma_f32_16x16x32_bf16 v[24:27], v[164:167], v[214:217], v[24:27]
	v_mfma_f32_16x16x32_bf16 v[16:19], v[172:175], v[214:217], v[16:19]
	v_mfma_f32_16x16x32_bf16 v[8:11], v[164:167], v[232:235], v[8:11]
	v_mfma_f32_16x16x32_bf16 v[0:3], v[172:175], v[232:235], v[0:3]
	v_mfma_f32_16x16x32_bf16 v[56:59], v[168:171], v[202:205], v[56:59]
	v_mfma_f32_16x16x32_bf16 v[48:51], v[194:197], v[202:205], v[48:51]
	v_mfma_f32_16x16x32_bf16 v[40:43], v[168:171], v[210:213], v[40:43]
	v_mfma_f32_16x16x32_bf16 v[32:35], v[194:197], v[210:213], v[32:35]
	v_mfma_f32_16x16x32_bf16 v[24:27], v[168:171], v[226:229], v[24:27]
	v_mfma_f32_16x16x32_bf16 v[16:19], v[194:197], v[226:229], v[16:19]
	v_mfma_f32_16x16x32_bf16 v[8:11], v[168:171], v[248:251], v[8:11]
	s_barrier
	v_mfma_f32_16x16x32_bf16 v[0:3], v[194:197], v[248:251], v[0:3]
	s_setprio 0
	s_add_i32 s82, s82, 2
	s_add_u32 s68, s68, 0x100
	s_addc_u32 s69, s69, 0
	s_add_u32 s80, s80, 0x100
	s_addc_u32 s81, s81, 0
	s_cmp_gt_u32 s82, 13
	s_cbranch_scc0 .LBB0_780
	s_and_b64 vcc, exec, s[40:41]
	s_cbranch_vccz .LBB0_783
	s_barrier
